# combo11 + first K-tile of UP/IN/EG/PL loops peeled: first MFMA into each accumulator takes srcC=0, accumulator zeroing moves removed
# speedup vs baseline: 1.0185x; 1.0114x over previous
; #define PG8_STAGE(bufoff, gbase, voff) do { _Pragma("unroll") for (int _i = 0; _i < 2; ++_i) \
;         __builtin_amdgcn_global_load_lds((const unsigned*)((const char*)(gbase) + (voff)[_i]), (PG8_LAS unsigned*)(lds + (bufoff) + ldsw + _i * 8192), 16, 0, 0); } while (0)
; #define PG8_LDA(dst, b, h) do { _Pragma("unroll") for (int m = 0; m < 4; ++m) _Pragma("unroll") for (int k = 0; k < 2; ++k) dst[m][k] = *(const PG8_LAS bf16x8*)(lds + PG8_SA(b, h) + aoff + m * 2048 + k * 1024); } while (0)
; #define PG8_LDB(dst, b, h) do { _Pragma("unroll") for (int n = 0; n < 2; ++n) _Pragma("unroll") for (int k = 0; k < 2; ++k) dst[n][k] = *(const PG8_LAS bf16x8*)(lds + PG8_SB(b, h) + boff + n * 2048 + k * 1024); } while (0)
; #define PG8_WAIT_V(n) asm volatile("s_waitcnt vmcnt(" #n ")" ::: "memory")
; #define PG8_WAIT_L(n) asm volatile("s_waitcnt lgkmcnt(" #n ")" ::: "memory")
; template <class Epi, class Sched, bool ALIGN_EPI = false, bool SP2 = false, bool ACHUNK = false>
; __device__ __forceinline__ void gemm_phase(PG8_LAS unsigned char* lds, const Gemm g, const Sched& S, const Epi& E) {
;     ...
;         const bool has_next = S.next(ui + 1, nxt);
;         const char* nA = has_next ? (const char*)g.A + (size_t)nxt.pm * tstepA : cA; const char* nB = has_next ? (const char*)g.Bt + (size_t)nxt.pn * tstepB : cB;
;         for (int t = 0; t < nt; t += 2) {
;             const bool last = (t == nt - 2);
;             if constexpr (Epi::HAS_MID) { if (t == Epi::MID_T) E.mid(acc, cur, wr, wc, fr, fq, ShflDev{}); }
;             const char* a1 = cA + (size_t)(t + 1) * kstep;
;             const char* a2 = last ? nA : cA + (size_t)(t + 2) * kstep; const char* b2 = last ? nB : cB + (size_t)(t + 2) * kstep;
;             const char* a3 = a2 + kstep; const char* b3 = b2 + kstep;
;             if (last && has_next) S.a_ready(nxt);
;             if constexpr (SP2) {
;             PG8_LDB(B0, 0, 0); PG8_LDB(B1, 0, 1); PG8_SCHED; PG8_LDA(At, 0, 0); PG8_STAGE(PG8_SA(1, 1), a1 + hstepA, voffA);
;             PG8_WAIT_V(8); PG8_WAIT_L(0); PG8_BAR; PG8_MMA(0, 0, At, B0); PG8_MMA(0, 1, At, B1); PG8_BAR; PG8_SCHED;
;             PG8_LDA(At, 0, 1); PG8_STAGE(PG8_SB(0, 0), b2, voffB); PG8_STAGE(PG8_SB(0, 1), b2 + hstepB, voffB); PG8_STAGE(PG8_SA(0, 0), a2, voffA);
;             PG8_WAIT_V(8); PG8_WAIT_L(0); PG8_BAR; PG8_MMA(1, 0, At, B0); PG8_MMA(1, 1, At, B1); PG8_BAR; PG8_SCHED;
.LBB0_106:
	s_andn2_b64 vcc, exec, s[44:45]
	s_nop 0
	s_cbranch_vccnz .LBB0_110
	s_add_u32 s8, s4, 0x100
	s_addc_u32 s9, s5, 0
	s_add_u32 s0, s6, 0x80
	s_addc_u32 s1, s7, 0
	s_mov_b32 s4, 0
	s_add_i32 s6, s4, 2
	s_add_u32 s7, s0, 0x80
	s_addc_u32 s5, s1, 0
	s_add_i32 s77, 0, 0x10000
	s_cmp_eq_u32 s54, s4
	s_cselect_b32 s5, s49, s5
	s_cselect_b32 s4, s48, s7
	v_add_u32_e32 v2, s77, v224
	s_cselect_b32 s79, s51, s9
	s_cselect_b32 s78, s50, s8
	s_add_i32 s7, 0, 0x14000
	s_waitcnt lgkmcnt(0)
	ds_read_b128 v[36:39], v2
	ds_read_b128 v[40:43], v2 offset:1024
	ds_read_b128 v[44:47], v2 offset:2048
	ds_read_b128 v[48:51], v2 offset:3072
	v_add_u32_e32 v2, s7, v224
	ds_read_b128 v[52:55], v2
	ds_read_b128 v[56:59], v2 offset:1024
	ds_read_b128 v[60:63], v2 offset:2048
	ds_read_b128 v[64:67], v2 offset:3072
	s_add_u32 s98, s0, s28
	s_addc_u32 s99, s1, s29
	s_add_i32 m0, s25, 0xc000
	ds_read_b128 v[164:167], v238
	ds_read_b128 v[168:171], v238 offset:1024
	ds_read_b128 v[184:187], v238 offset:2048
	ds_read_b128 v[188:191], v238 offset:3072
	ds_read_b128 v[198:201], v238 offset:4096
	ds_read_b128 v[202:205], v238 offset:5120
	ds_read_b128 v[206:209], v238 offset:6144
	ds_read_b128 v[210:213], v238 offset:7168
	global_load_lds_dwordx4 v172, s[98:99]
	s_add_i32 m0, s25, 0xe000
	s_nop 0
	global_load_lds_dwordx4 v176, s[98:99]
	s_waitcnt vmcnt(8)
	s_waitcnt lgkmcnt(0)
	s_barrier
	s_setprio 1
	v_mfma_f32_16x16x32_bf16 v[148:151], v[36:39], v[164:167], 0
	v_mfma_f32_16x16x32_bf16 v[152:155], v[44:47], v[164:167], 0
	v_mfma_f32_16x16x32_bf16 v[132:135], v[36:39], v[184:187], 0
	v_mfma_f32_16x16x32_bf16 v[140:143], v[44:47], v[184:187], 0
	v_mfma_f32_16x16x32_bf16 v[136:139], v[36:39], v[198:201], 0
	v_mfma_f32_16x16x32_bf16 v[144:147], v[44:47], v[198:201], 0
	v_mfma_f32_16x16x32_bf16 v[160:163], v[36:39], v[206:209], 0
	v_mfma_f32_16x16x32_bf16 v[156:159], v[44:47], v[206:209], 0
	v_mfma_f32_16x16x32_bf16 v[148:151], v[40:43], v[168:171], v[148:151]
	v_mfma_f32_16x16x32_bf16 v[152:155], v[48:51], v[168:171], v[152:155]
	v_mfma_f32_16x16x32_bf16 v[132:135], v[40:43], v[188:191], v[132:135]
	v_mfma_f32_16x16x32_bf16 v[140:143], v[48:51], v[188:191], v[140:143]
	v_mfma_f32_16x16x32_bf16 v[136:139], v[40:43], v[202:205], v[136:139]
	v_mfma_f32_16x16x32_bf16 v[144:147], v[48:51], v[202:205], v[144:147]
	v_mfma_f32_16x16x32_bf16 v[160:163], v[40:43], v[210:213], v[160:163]
	v_mfma_f32_16x16x32_bf16 v[156:159], v[48:51], v[210:213], v[156:159]
	s_setprio 0
	s_setprio 1
	v_mfma_f32_16x16x32_bf16 v[124:127], v[52:55], v[164:167], 0
	v_mfma_f32_16x16x32_bf16 v[128:131], v[60:63], v[164:167], 0
	v_mfma_f32_16x16x32_bf16 v[116:119], v[52:55], v[184:187], 0
	v_mfma_f32_16x16x32_bf16 v[120:123], v[60:63], v[184:187], 0
	v_mfma_f32_16x16x32_bf16 v[112:115], v[52:55], v[198:201], 0
	v_mfma_f32_16x16x32_bf16 v[108:111], v[60:63], v[198:201], 0
	v_mfma_f32_16x16x32_bf16 v[104:107], v[52:55], v[206:209], 0
	v_mfma_f32_16x16x32_bf16 v[100:103], v[60:63], v[206:209], 0
	v_mfma_f32_16x16x32_bf16 v[124:127], v[56:59], v[168:171], v[124:127]
	v_mfma_f32_16x16x32_bf16 v[128:131], v[64:67], v[168:171], v[128:131]
	v_mfma_f32_16x16x32_bf16 v[116:119], v[56:59], v[188:191], v[116:119]
	v_mfma_f32_16x16x32_bf16 v[120:123], v[64:67], v[188:191], v[120:123]
	v_mfma_f32_16x16x32_bf16 v[112:115], v[56:59], v[202:205], v[112:115]
	v_mfma_f32_16x16x32_bf16 v[108:111], v[64:67], v[202:205], v[108:111]
	v_mfma_f32_16x16x32_bf16 v[104:107], v[56:59], v[210:213], v[104:107]
	v_mfma_f32_16x16x32_bf16 v[100:103], v[64:67], v[210:213], v[100:103]
	s_setprio 0
	s_barrier
	s_add_i32 s77, s77, s17
	s_add_u32 s98, s78, s18
	s_addc_u32 s99, s79, s19
	s_mov_b32 m0, s77
	ds_read_b128 v[164:167], v238 offset:16384
	ds_read_b128 v[168:171], v238 offset:17408
	ds_read_b128 v[184:187], v238 offset:18432
	ds_read_b128 v[188:191], v238 offset:19456
	ds_read_b128 v[198:201], v238 offset:20480
	ds_read_b128 v[202:205], v238 offset:21504
	ds_read_b128 v[206:209], v238 offset:22528
	ds_read_b128 v[210:213], v238 offset:23552
	global_load_lds_dwordx4 v174, s[78:79]
	s_add_i32 m0, s77, 0x2000
	s_add_i32 s7, s7, s17
	global_load_lds_dwordx4 v178, s[78:79]
	s_mov_b32 m0, s7
	s_nop 0
	global_load_lds_dwordx4 v174, s[98:99]
	s_add_i32 m0, s7, 0x2000
	s_nop 0
	global_load_lds_dwordx4 v178, s[98:99]
	s_mov_b32 m0, s25
	s_nop 0
	global_load_lds_dwordx4 v172, s[4:5]
	s_mov_b32 m0, s26
	s_nop 0
	global_load_lds_dwordx4 v176, s[4:5]
	s_waitcnt vmcnt(8)
	s_waitcnt lgkmcnt(0)
	s_barrier
	s_setprio 1
	v_mfma_f32_16x16x32_bf16 v[96:99], v[36:39], v[164:167], 0
	v_mfma_f32_16x16x32_bf16 v[92:95], v[44:47], v[164:167], 0
	v_mfma_f32_16x16x32_bf16 v[88:91], v[36:39], v[184:187], 0
	v_mfma_f32_16x16x32_bf16 v[84:87], v[44:47], v[184:187], 0
	v_mfma_f32_16x16x32_bf16 v[80:83], v[36:39], v[198:201], 0
	v_mfma_f32_16x16x32_bf16 v[76:79], v[44:47], v[198:201], 0
	v_mfma_f32_16x16x32_bf16 v[36:39], v[36:39], v[206:209], 0
	v_mfma_f32_16x16x32_bf16 v[96:99], v[40:43], v[168:171], v[96:99]
	v_mfma_f32_16x16x32_bf16 v[92:95], v[48:51], v[168:171], v[92:95]
	v_mfma_f32_16x16x32_bf16 v[88:91], v[40:43], v[188:191], v[88:91]
	v_mfma_f32_16x16x32_bf16 v[84:87], v[48:51], v[188:191], v[84:87]
	v_mfma_f32_16x16x32_bf16 v[80:83], v[40:43], v[202:205], v[80:83]
	v_mfma_f32_16x16x32_bf16 v[76:79], v[48:51], v[202:205], v[76:79]
	v_mfma_f32_16x16x32_bf16 v[36:39], v[40:43], v[210:213], v[36:39]
	v_mfma_f32_16x16x32_bf16 v[40:43], v[44:47], v[206:209], 0
	v_mfma_f32_16x16x32_bf16 v[40:43], v[48:51], v[210:213], v[40:43]
	s_setprio 0
	s_setprio 1
	v_mfma_f32_16x16x32_bf16 v[28:31], v[52:55], v[164:167], 0
	v_mfma_f32_16x16x32_bf16 v[32:35], v[60:63], v[164:167], 0
	v_mfma_f32_16x16x32_bf16 v[20:23], v[52:55], v[184:187], 0
	v_mfma_f32_16x16x32_bf16 v[24:27], v[60:63], v[184:187], 0
	v_mfma_f32_16x16x32_bf16 v[16:19], v[52:55], v[198:201], 0
	v_mfma_f32_16x16x32_bf16 v[12:15], v[60:63], v[198:201], 0
	v_mfma_f32_16x16x32_bf16 v[8:11], v[52:55], v[206:209], 0
	v_mfma_f32_16x16x32_bf16 v[4:7], v[60:63], v[206:209], 0
	v_mfma_f32_16x16x32_bf16 v[28:31], v[56:59], v[168:171], v[28:31]
	v_mfma_f32_16x16x32_bf16 v[32:35], v[64:67], v[168:171], v[32:35]
	v_mfma_f32_16x16x32_bf16 v[20:23], v[56:59], v[188:191], v[20:23]
	v_mfma_f32_16x16x32_bf16 v[24:27], v[64:67], v[188:191], v[24:27]
	v_mfma_f32_16x16x32_bf16 v[16:19], v[56:59], v[202:205], v[16:19]
	v_mfma_f32_16x16x32_bf16 v[12:15], v[64:67], v[202:205], v[12:15]
	v_mfma_f32_16x16x32_bf16 v[8:11], v[56:59], v[210:213], v[8:11]
	v_mfma_f32_16x16x32_bf16 v[4:7], v[64:67], v[210:213], v[4:7]
	s_setprio 0
	s_barrier
	s_branch .Lpe_join_108

; #define PG8_STAGE(bufoff, gbase, voff) do { _Pragma("unroll") for (int _i = 0; _i < 2; ++_i) \
;         __builtin_amdgcn_global_load_lds((const unsigned*)((const char*)(gbase) + (voff)[_i]), (PG8_LAS unsigned*)(lds + (bufoff) + ldsw + _i * 8192), 16, 0, 0); } while (0)
; #define PG8_LDA(dst, b, h) do { _Pragma("unroll") for (int m = 0; m < 4; ++m) _Pragma("unroll") for (int k = 0; k < 2; ++k) dst[m][k] = *(const PG8_LAS bf16x8*)(lds + PG8_SA(b, h) + aoff + m * 2048 + k * 1024); } while (0)
; #define PG8_LDB(dst, b, h) do { _Pragma("unroll") for (int n = 0; n < 2; ++n) _Pragma("unroll") for (int k = 0; k < 2; ++k) dst[n][k] = *(const PG8_LAS bf16x8*)(lds + PG8_SB(b, h) + boff + n * 2048 + k * 1024); } while (0)
; #define PG8_MMA(ai, bj, At, Bt) do { __builtin_amdgcn_s_setprio(1); _Pragma("unroll") for (int m = 0; m < 4; ++m) _Pragma("unroll") for (int n = 0; n < 2; ++n) _Pragma("unroll") for (int k = 0; k < 2; ++k) \
;         acc[ai][bj][m][n] = __builtin_amdgcn_mfma_f32_16x16x32_bf16(Bt[n][k], At[m][k], acc[ai][bj][m][n], 0, 0, 0); __builtin_amdgcn_s_setprio(0); } while (0)
; #define PG8_WAIT_V(n) asm volatile("s_waitcnt vmcnt(" #n ")" ::: "memory")
; #define PG8_WAIT_L(n) asm volatile("s_waitcnt lgkmcnt(" #n ")" ::: "memory")
; #define PG8_BAR __builtin_amdgcn_s_barrier()
; #define PG8_SCHED __builtin_amdgcn_sched_barrier(0)
; template <class Epi, class Sched, bool ALIGN_EPI = false, bool SP2 = false, bool ACHUNK = false>
; __device__ __forceinline__ void gemm_phase(PG8_LAS unsigned char* lds, const Gemm g, const Sched& S, const Epi& E) {
;     ...
;             PG8_LDB(B0, 1, 0); PG8_LDB(B1, 1, 1); PG8_SCHED; PG8_LDA(At, 1, 0); PG8_STAGE(PG8_SA(0, 1), a2 + hstepA, voffA);
;             PG8_WAIT_V(8); PG8_WAIT_L(0); PG8_BAR; PG8_MMA(0, 0, At, B0); PG8_MMA(0, 1, At, B1); PG8_BAR; PG8_SCHED;
;             PG8_LDA(At, 1, 1); PG8_STAGE(PG8_SB(1, 0), b3, voffB); PG8_STAGE(PG8_SB(1, 1), b3 + hstepB, voffB); PG8_STAGE(PG8_SA(1, 0), a3, voffA);
;             PG8_WAIT_V(8); PG8_WAIT_L(0); PG8_BAR; PG8_MMA(1, 0, At, B0); PG8_MMA(1, 1, At, B1); PG8_BAR; PG8_SCHED;
.Lpe_join_108:
	s_add_i32 s7, 0, 0x18000
	v_add_u32_e32 v2, s7, v224
	s_add_i32 s77, 0, 0x1c000
	ds_read_b128 v[44:47], v2
	ds_read_b128 v[48:51], v2 offset:1024
	ds_read_b128 v[52:55], v2 offset:2048
	ds_read_b128 v[56:59], v2 offset:3072
	v_add_u32_e32 v2, s77, v224
	ds_read_b128 v[60:63], v2
	ds_read_b128 v[64:67], v2 offset:1024
	ds_read_b128 v[164:167], v2 offset:2048
	ds_read_b128 v[168:171], v2 offset:3072
	s_add_u32 s4, s4, s28
	s_addc_u32 s5, s5, s29
	s_mov_b32 m0, s27
	ds_read_b128 v[68:71], v238 offset:32768
	ds_read_b128 v[72:75], v238 offset:33792
	ds_read_b128 v[184:187], v238 offset:34816
	ds_read_b128 v[188:191], v238 offset:35840
	ds_read_b128 v[198:201], v238 offset:36864
	ds_read_b128 v[202:205], v238 offset:37888
	ds_read_b128 v[206:209], v238 offset:38912
	ds_read_b128 v[210:213], v238 offset:39936
	global_load_lds_dwordx4 v172, s[4:5]
	s_mov_b32 m0, s36
	s_nop 0
	global_load_lds_dwordx4 v176, s[4:5]
	s_waitcnt vmcnt(8)
	s_waitcnt lgkmcnt(0)
	s_barrier
	s_setprio 1
	v_mfma_f32_16x16x32_bf16 v[148:151], v[44:47], v[68:71], v[148:151]
	v_mfma_f32_16x16x32_bf16 v[152:155], v[52:55], v[68:71], v[152:155]
	v_mfma_f32_16x16x32_bf16 v[132:135], v[44:47], v[184:187], v[132:135]
	v_mfma_f32_16x16x32_bf16 v[140:143], v[52:55], v[184:187], v[140:143]
	v_mfma_f32_16x16x32_bf16 v[136:139], v[44:47], v[198:201], v[136:139]
	v_mfma_f32_16x16x32_bf16 v[144:147], v[52:55], v[198:201], v[144:147]
	v_mfma_f32_16x16x32_bf16 v[160:163], v[44:47], v[206:209], v[160:163]
	v_mfma_f32_16x16x32_bf16 v[156:159], v[52:55], v[206:209], v[156:159]
	v_mfma_f32_16x16x32_bf16 v[148:151], v[48:51], v[72:75], v[148:151]
	v_mfma_f32_16x16x32_bf16 v[152:155], v[56:59], v[72:75], v[152:155]
	v_mfma_f32_16x16x32_bf16 v[132:135], v[48:51], v[188:191], v[132:135]
	v_mfma_f32_16x16x32_bf16 v[140:143], v[56:59], v[188:191], v[140:143]
	v_mfma_f32_16x16x32_bf16 v[136:139], v[48:51], v[202:205], v[136:139]
	v_mfma_f32_16x16x32_bf16 v[144:147], v[56:59], v[202:205], v[144:147]
	v_mfma_f32_16x16x32_bf16 v[160:163], v[48:51], v[210:213], v[160:163]
	v_mfma_f32_16x16x32_bf16 v[156:159], v[56:59], v[210:213], v[156:159]
	s_setprio 0
	s_setprio 1
	v_mfma_f32_16x16x32_bf16 v[124:127], v[60:63], v[68:71], v[124:127]
	v_mfma_f32_16x16x32_bf16 v[68:71], v[164:167], v[68:71], v[128:131]
	v_mfma_f32_16x16x32_bf16 v[128:131], v[168:171], v[72:75], v[68:71]
	v_mfma_f32_16x16x32_bf16 v[68:71], v[60:63], v[184:187], v[116:119]
	v_mfma_f32_16x16x32_bf16 v[116:119], v[64:67], v[188:191], v[68:71]
	v_mfma_f32_16x16x32_bf16 v[68:71], v[164:167], v[184:187], v[120:123]
	v_mfma_f32_16x16x32_bf16 v[120:123], v[168:171], v[188:191], v[68:71]
	v_mfma_f32_16x16x32_bf16 v[68:71], v[60:63], v[198:201], v[112:115]
	v_mfma_f32_16x16x32_bf16 v[112:115], v[64:67], v[202:205], v[68:71]
	v_mfma_f32_16x16x32_bf16 v[68:71], v[164:167], v[198:201], v[108:111]
	v_mfma_f32_16x16x32_bf16 v[108:111], v[168:171], v[202:205], v[68:71]
	v_mfma_f32_16x16x32_bf16 v[68:71], v[60:63], v[206:209], v[104:107]
	v_mfma_f32_16x16x32_bf16 v[104:107], v[64:67], v[210:213], v[68:71]
	v_mfma_f32_16x16x32_bf16 v[68:71], v[164:167], v[206:209], v[100:103]
	v_mfma_f32_16x16x32_bf16 v[124:127], v[64:67], v[72:75], v[124:127]
	v_mfma_f32_16x16x32_bf16 v[100:103], v[168:171], v[210:213], v[68:71]
	s_setprio 0
	s_barrier
	s_sub_u32 s4, s4, s28
	s_subb_u32 s5, s5, s29
	s_add_u32 s4, s4, s10
	s_addc_u32 s5, s5, s11
	s_add_u32 s78, s78, s10
	s_addc_u32 s79, s79, s11
	s_add_u32 s98, s98, s10
	s_addc_u32 s99, s99, s11
	s_add_i32 m0, s7, s17
	ds_read_b128 v[184:187], v238 offset:49152
	ds_read_b128 v[188:191], v238 offset:50176
	ds_read_b128 v[198:201], v238 offset:51200
	ds_read_b128 v[202:205], v238 offset:52224
	ds_read_b128 v[206:209], v238 offset:53248
	ds_read_b128 v[210:213], v238 offset:54272
	ds_read_b128 v[214:217], v238 offset:55296
	ds_read_b128 v[218:221], v238 offset:56320
	global_load_lds_dwordx4 v174, s[78:79]
	s_add_i32 m0, m0, 0x2000
	s_nop 0
	global_load_lds_dwordx4 v178, s[78:79]
	s_add_i32 m0, s77, s17
	s_nop 0
	global_load_lds_dwordx4 v174, s[98:99]
	s_add_i32 m0, m0, 0x2000
	s_nop 0
	global_load_lds_dwordx4 v178, s[98:99]
	s_mov_b32 m0, s52
	s_nop 0
	global_load_lds_dwordx4 v172, s[4:5]
	s_mov_b32 m0, s53
	s_nop 0
	global_load_lds_dwordx4 v176, s[4:5]
	s_waitcnt vmcnt(8)
	s_waitcnt lgkmcnt(0)
	s_barrier
	s_setprio 1
	v_mfma_f32_16x16x32_bf16 v[68:71], v[44:47], v[184:187], v[96:99]
	v_mfma_f32_16x16x32_bf16 v[96:99], v[48:51], v[188:191], v[68:71]
	v_mfma_f32_16x16x32_bf16 v[68:71], v[52:55], v[184:187], v[92:95]
	v_mfma_f32_16x16x32_bf16 v[92:95], v[56:59], v[188:191], v[68:71]
	v_mfma_f32_16x16x32_bf16 v[68:71], v[44:47], v[198:201], v[88:91]
	v_mfma_f32_16x16x32_bf16 v[88:91], v[48:51], v[202:205], v[68:71]
	v_mfma_f32_16x16x32_bf16 v[68:71], v[52:55], v[198:201], v[84:87]
	v_mfma_f32_16x16x32_bf16 v[84:87], v[56:59], v[202:205], v[68:71]
	v_mfma_f32_16x16x32_bf16 v[68:71], v[44:47], v[206:209], v[80:83]
	v_mfma_f32_16x16x32_bf16 v[36:39], v[44:47], v[214:217], v[36:39]
	v_mfma_f32_16x16x32_bf16 v[80:83], v[48:51], v[210:213], v[68:71]
	v_mfma_f32_16x16x32_bf16 v[68:71], v[52:55], v[206:209], v[76:79]
	v_mfma_f32_16x16x32_bf16 v[72:75], v[48:51], v[218:221], v[36:39]
	v_mfma_f32_16x16x32_bf16 v[36:39], v[52:55], v[214:217], v[40:43]
	v_mfma_f32_16x16x32_bf16 v[76:79], v[56:59], v[210:213], v[68:71]
	v_mfma_f32_16x16x32_bf16 v[68:71], v[56:59], v[218:221], v[36:39]
	s_setprio 0
	s_setprio 1
	v_mfma_f32_16x16x32_bf16 v[28:31], v[60:63], v[184:187], v[28:31]
	v_mfma_f32_16x16x32_bf16 v[32:35], v[164:167], v[184:187], v[32:35]
	v_mfma_f32_16x16x32_bf16 v[20:23], v[60:63], v[198:201], v[20:23]
	v_mfma_f32_16x16x32_bf16 v[24:27], v[164:167], v[198:201], v[24:27]
	v_mfma_f32_16x16x32_bf16 v[16:19], v[60:63], v[206:209], v[16:19]
	v_mfma_f32_16x16x32_bf16 v[12:15], v[164:167], v[206:209], v[12:15]
	v_mfma_f32_16x16x32_bf16 v[8:11], v[60:63], v[214:217], v[8:11]
	v_mfma_f32_16x16x32_bf16 v[4:7], v[164:167], v[214:217], v[4:7]
	v_mfma_f32_16x16x32_bf16 v[28:31], v[64:67], v[188:191], v[28:31]
	v_mfma_f32_16x16x32_bf16 v[32:35], v[168:171], v[188:191], v[32:35]
	v_mfma_f32_16x16x32_bf16 v[20:23], v[64:67], v[202:205], v[20:23]
	v_mfma_f32_16x16x32_bf16 v[24:27], v[168:171], v[202:205], v[24:27]
	v_mfma_f32_16x16x32_bf16 v[16:19], v[64:67], v[210:213], v[16:19]
	v_mfma_f32_16x16x32_bf16 v[12:15], v[168:171], v[210:213], v[12:15]
	v_mfma_f32_16x16x32_bf16 v[8:11], v[64:67], v[218:221], v[8:11]
	v_mfma_f32_16x16x32_bf16 v[4:7], v[168:171], v[218:221], v[4:7]
	s_setprio 0
	s_barrier
	s_add_u32 s8, s8, 0x100
	s_addc_u32 s9, s9, 0
	s_add_u32 s0, s0, 0x100
	s_addc_u32 s1, s1, 0
	s_cmp_ge_i32 s6, s37
	s_mov_b32 s4, s6
	s_cbranch_scc0 .LBB0_108
	v_readlane_b32 s78, v254, 23
	v_readlane_b32 s79, v254, 24

; #define PG8_STAGE(bufoff, gbase, voff) do { _Pragma("unroll") for (int _i = 0; _i < 2; ++_i) \
;         __builtin_amdgcn_global_load_lds((const unsigned*)((const char*)(gbase) + (voff)[_i]), (PG8_LAS unsigned*)(lds + (bufoff) + ldsw + _i * 8192), 16, 0, 0); } while (0)
; #define PG8_LDA(dst, b, h) do { _Pragma("unroll") for (int m = 0; m < 4; ++m) _Pragma("unroll") for (int k = 0; k < 2; ++k) dst[m][k] = *(const PG8_LAS bf16x8*)(lds + PG8_SA(b, h) + aoff + m * 2048 + k * 1024); } while (0)
; #define PG8_LDB(dst, b, h) do { _Pragma("unroll") for (int n = 0; n < 2; ++n) _Pragma("unroll") for (int k = 0; k < 2; ++k) dst[n][k] = *(const PG8_LAS bf16x8*)(lds + PG8_SB(b, h) + boff + n * 2048 + k * 1024); } while (0)
; #define PG8_WAIT_V(n) asm volatile("s_waitcnt vmcnt(" #n ")" ::: "memory")
; #define PG8_WAIT_L(n) asm volatile("s_waitcnt lgkmcnt(" #n ")" ::: "memory")
; template <class Epi, class Sched, bool ALIGN_EPI = false, bool SP2 = false, bool ACHUNK = false>
; __device__ __forceinline__ void gemm_phase(PG8_LAS unsigned char* lds, const Gemm g, const Sched& S, const Epi& E) {
;     ...
;         const bool has_next = S.next(ui + 1, nxt);
;         const char* nA = has_next ? (const char*)g.A + (size_t)nxt.pm * tstepA : cA; const char* nB = has_next ? (const char*)g.Bt + (size_t)nxt.pn * tstepB : cB;
;         for (int t = 0; t < nt; t += 2) {
;             const bool last = (t == nt - 2);
;             if constexpr (Epi::HAS_MID) { if (t == Epi::MID_T) E.mid(acc, cur, wr, wc, fr, fq, ShflDev{}); }
;             const char* a1 = cA + (size_t)(t + 1) * kstep;
;             const char* a2 = last ? nA : cA + (size_t)(t + 2) * kstep; const char* b2 = last ? nB : cB + (size_t)(t + 2) * kstep;
;             const char* a3 = a2 + kstep; const char* b3 = b2 + kstep;
;             if (last && has_next) S.a_ready(nxt);
;             if constexpr (SP2) {
;             PG8_LDB(B0, 0, 0); PG8_LDB(B1, 0, 1); PG8_SCHED; PG8_LDA(At, 0, 0); PG8_STAGE(PG8_SA(1, 1), a1 + hstepA, voffA);
;             PG8_WAIT_V(8); PG8_WAIT_L(0); PG8_BAR; PG8_MMA(0, 0, At, B0); PG8_MMA(0, 1, At, B1); PG8_BAR; PG8_SCHED;
;             PG8_LDA(At, 0, 1); PG8_STAGE(PG8_SB(0, 0), b2, voffB); PG8_STAGE(PG8_SB(0, 1), b2 + hstepB, voffB); PG8_STAGE(PG8_SA(0, 0), a2, voffA);
;             PG8_WAIT_V(8); PG8_WAIT_L(0); PG8_BAR; PG8_MMA(1, 0, At, B0); PG8_MMA(1, 1, At, B1); PG8_BAR; PG8_SCHED;
.LBB0_351:
	s_andn2_b64 vcc, exec, s[4:5]
	s_cbranch_vccnz .LBB0_342
	s_add_u32 s40, s18, 0x100
	s_addc_u32 s41, s19, 0
	s_add_u32 s18, s20, 0x80
	s_addc_u32 s19, s21, 0
	s_mov_b32 s20, 0
	s_add_i32 s42, s20, 2
	s_add_u32 s43, s18, 0x80
	s_addc_u32 s21, s19, 0
	s_add_i32 s46, 0, 0x10000
	s_cmp_eq_u32 s33, s20
	s_cselect_b32 s21, s13, s21
	s_cselect_b32 s20, s12, s43
	v_add_u32_e32 v153, s46, v143
	s_cselect_b32 s45, s17, s41
	s_cselect_b32 s44, s16, s40
	s_add_i32 s43, 0, 0x14000
	ds_read_b128 v[154:157], v153
	ds_read_b128 v[158:161], v153 offset:1024
	ds_read_b128 v[162:165], v153 offset:2048
	ds_read_b128 v[166:169], v153 offset:3072
	v_add_u32_e32 v153, s43, v143
	ds_read_b128 v[170:173], v153
	ds_read_b128 v[174:177], v153 offset:1024
	ds_read_b128 v[178:181], v153 offset:2048
	ds_read_b128 v[182:185], v153 offset:3072
	s_add_i32 m0, s25, 0xc000
	ds_read_b128 v[186:189], v152
	ds_read_b128 v[190:193], v152 offset:1024
	ds_read_b128 v[198:201], v152 offset:2048
	ds_read_b128 v[202:205], v152 offset:3072
	ds_read_b128 v[206:209], v152 offset:4096
	ds_read_b128 v[210:213], v152 offset:5120
	ds_read_b128 v[214:217], v152 offset:6144
	ds_read_b128 v[218:221], v152 offset:7168
	global_load_lds_dwordx4 v138, s[18:19]
	s_add_i32 m0, s25, 0xe000
	s_nop 0
	global_load_lds_dwordx4 v140, s[18:19]
	s_waitcnt vmcnt(8)
	s_waitcnt lgkmcnt(0)
	s_barrier
	s_setprio 1
	v_mfma_f32_16x16x32_bf16 v[124:127], v[154:157], v[186:189], 0
	v_mfma_f32_16x16x32_bf16 v[128:131], v[162:165], v[186:189], 0
	v_mfma_f32_16x16x32_bf16 v[112:115], v[154:157], v[198:201], 0
	v_mfma_f32_16x16x32_bf16 v[108:111], v[162:165], v[198:201], 0
	v_mfma_f32_16x16x32_bf16 v[96:99], v[154:157], v[206:209], 0
	v_mfma_f32_16x16x32_bf16 v[92:95], v[162:165], v[206:209], 0
	v_mfma_f32_16x16x32_bf16 v[80:83], v[154:157], v[214:217], 0
	v_mfma_f32_16x16x32_bf16 v[76:79], v[162:165], v[214:217], 0
	v_mfma_f32_16x16x32_bf16 v[124:127], v[158:161], v[190:193], v[124:127]
	v_mfma_f32_16x16x32_bf16 v[128:131], v[166:169], v[190:193], v[128:131]
	v_mfma_f32_16x16x32_bf16 v[112:115], v[158:161], v[202:205], v[112:115]
	v_mfma_f32_16x16x32_bf16 v[108:111], v[166:169], v[202:205], v[108:111]
	v_mfma_f32_16x16x32_bf16 v[96:99], v[158:161], v[210:213], v[96:99]
	v_mfma_f32_16x16x32_bf16 v[92:95], v[166:169], v[210:213], v[92:95]
	v_mfma_f32_16x16x32_bf16 v[80:83], v[158:161], v[218:221], v[80:83]
	v_mfma_f32_16x16x32_bf16 v[76:79], v[166:169], v[218:221], v[76:79]
	s_setprio 0
	s_setprio 1
	v_mfma_f32_16x16x32_bf16 v[120:123], v[170:173], v[186:189], 0
	v_mfma_f32_16x16x32_bf16 v[116:119], v[178:181], v[186:189], 0
	v_mfma_f32_16x16x32_bf16 v[104:107], v[170:173], v[198:201], 0
	v_mfma_f32_16x16x32_bf16 v[100:103], v[178:181], v[198:201], 0
	v_mfma_f32_16x16x32_bf16 v[88:91], v[170:173], v[206:209], 0
	v_mfma_f32_16x16x32_bf16 v[84:87], v[178:181], v[206:209], 0
	v_mfma_f32_16x16x32_bf16 v[72:75], v[170:173], v[214:217], 0
	v_mfma_f32_16x16x32_bf16 v[68:71], v[178:181], v[214:217], 0
	v_mfma_f32_16x16x32_bf16 v[120:123], v[174:177], v[190:193], v[120:123]
	v_mfma_f32_16x16x32_bf16 v[116:119], v[182:185], v[190:193], v[116:119]
	v_mfma_f32_16x16x32_bf16 v[104:107], v[174:177], v[202:205], v[104:107]
	v_mfma_f32_16x16x32_bf16 v[100:103], v[182:185], v[202:205], v[100:103]
	v_mfma_f32_16x16x32_bf16 v[88:91], v[174:177], v[210:213], v[88:91]
	v_mfma_f32_16x16x32_bf16 v[84:87], v[182:185], v[210:213], v[84:87]
	v_mfma_f32_16x16x32_bf16 v[72:75], v[174:177], v[218:221], v[72:75]
	v_mfma_f32_16x16x32_bf16 v[68:71], v[182:185], v[218:221], v[68:71]
	s_setprio 0
	s_barrier
	s_add_i32 s46, s46, s24
	s_mov_b32 m0, s46
	ds_read_b128 v[186:189], v152 offset:16384
	ds_read_b128 v[190:193], v152 offset:17408
	ds_read_b128 v[198:201], v152 offset:18432
	ds_read_b128 v[202:205], v152 offset:19456
	ds_read_b128 v[206:209], v152 offset:20480
	ds_read_b128 v[210:213], v152 offset:21504
	ds_read_b128 v[214:217], v152 offset:22528
	ds_read_b128 v[218:221], v152 offset:23552
	global_load_lds_dwordx4 v2, s[44:45]
	s_add_i32 m0, s46, 0x2000
	s_add_i32 s43, s43, s24
	global_load_lds_dwordx4 v136, s[44:45]
	s_add_u32 s44, s44, s0
	s_addc_u32 s45, s45, s1
	s_mov_b64 vcc, s[44:45]
	s_sub_u32 s98, s44, s0
	s_subb_u32 s99, s45, s1
	s_mov_b32 m0, s43
	s_nop 0
	global_load_lds_dwordx4 v2, s[44:45]
	s_add_i32 m0, s43, 0x2000
	s_nop 0
	global_load_lds_dwordx4 v136, s[44:45]
	s_mov_b32 m0, s25
	s_nop 0
	global_load_lds_dwordx4 v132, s[20:21]
	s_mov_b32 m0, s26
	s_nop 0
	global_load_lds_dwordx4 v134, s[20:21]
	s_waitcnt vmcnt(8)
	s_waitcnt lgkmcnt(0)
	s_barrier
	s_setprio 1
	v_mfma_f32_16x16x32_bf16 v[64:67], v[154:157], v[186:189], 0
	v_mfma_f32_16x16x32_bf16 v[60:63], v[162:165], v[186:189], 0
	v_mfma_f32_16x16x32_bf16 v[48:51], v[154:157], v[198:201], 0
	v_mfma_f32_16x16x32_bf16 v[44:47], v[162:165], v[198:201], 0
	v_mfma_f32_16x16x32_bf16 v[32:35], v[154:157], v[206:209], 0
	v_mfma_f32_16x16x32_bf16 v[28:31], v[162:165], v[206:209], 0
	v_mfma_f32_16x16x32_bf16 v[16:19], v[154:157], v[214:217], 0
	v_mfma_f32_16x16x32_bf16 v[12:15], v[162:165], v[214:217], 0
	v_mfma_f32_16x16x32_bf16 v[64:67], v[158:161], v[190:193], v[64:67]
	v_mfma_f32_16x16x32_bf16 v[60:63], v[166:169], v[190:193], v[60:63]
	v_mfma_f32_16x16x32_bf16 v[48:51], v[158:161], v[202:205], v[48:51]
	v_mfma_f32_16x16x32_bf16 v[44:47], v[166:169], v[202:205], v[44:47]
	v_mfma_f32_16x16x32_bf16 v[32:35], v[158:161], v[210:213], v[32:35]
	v_mfma_f32_16x16x32_bf16 v[28:31], v[166:169], v[210:213], v[28:31]
	v_mfma_f32_16x16x32_bf16 v[16:19], v[158:161], v[218:221], v[16:19]
	v_mfma_f32_16x16x32_bf16 v[12:15], v[166:169], v[218:221], v[12:15]
	s_setprio 0
	s_setprio 1
	v_mfma_f32_16x16x32_bf16 v[56:59], v[170:173], v[186:189], 0
	v_mfma_f32_16x16x32_bf16 v[52:55], v[178:181], v[186:189], 0
	v_mfma_f32_16x16x32_bf16 v[40:43], v[170:173], v[198:201], 0
	v_mfma_f32_16x16x32_bf16 v[36:39], v[178:181], v[198:201], 0
	v_mfma_f32_16x16x32_bf16 v[24:27], v[170:173], v[206:209], 0
	v_mfma_f32_16x16x32_bf16 v[20:23], v[178:181], v[206:209], 0
	v_mfma_f32_16x16x32_bf16 v[8:11], v[170:173], v[214:217], 0
	v_mfma_f32_16x16x32_bf16 v[4:7], v[178:181], v[214:217], 0
	v_mfma_f32_16x16x32_bf16 v[56:59], v[174:177], v[190:193], v[56:59]
	v_mfma_f32_16x16x32_bf16 v[52:55], v[182:185], v[190:193], v[52:55]
	v_mfma_f32_16x16x32_bf16 v[40:43], v[174:177], v[202:205], v[40:43]
	v_mfma_f32_16x16x32_bf16 v[36:39], v[182:185], v[202:205], v[36:39]
	v_mfma_f32_16x16x32_bf16 v[24:27], v[174:177], v[210:213], v[24:27]
	v_mfma_f32_16x16x32_bf16 v[20:23], v[182:185], v[210:213], v[20:23]
	v_mfma_f32_16x16x32_bf16 v[8:11], v[174:177], v[218:221], v[8:11]
	v_mfma_f32_16x16x32_bf16 v[4:7], v[182:185], v[218:221], v[4:7]
	s_setprio 0
	s_barrier
	s_branch .Lpe_join_353

; #define PG8_STAGE(bufoff, gbase, voff) do { _Pragma("unroll") for (int _i = 0; _i < 2; ++_i) \
;         __builtin_amdgcn_global_load_lds((const unsigned*)((const char*)(gbase) + (voff)[_i]), (PG8_LAS unsigned*)(lds + (bufoff) + ldsw + _i * 8192), 16, 0, 0); } while (0)
; #define PG8_LDA(dst, b, h) do { _Pragma("unroll") for (int m = 0; m < 4; ++m) _Pragma("unroll") for (int k = 0; k < 2; ++k) dst[m][k] = *(const PG8_LAS bf16x8*)(lds + PG8_SA(b, h) + aoff + m * 2048 + k * 1024); } while (0)
; #define PG8_LDB(dst, b, h) do { _Pragma("unroll") for (int n = 0; n < 2; ++n) _Pragma("unroll") for (int k = 0; k < 2; ++k) dst[n][k] = *(const PG8_LAS bf16x8*)(lds + PG8_SB(b, h) + boff + n * 2048 + k * 1024); } while (0)
; #define PG8_MMA(ai, bj, At, Bt) do { __builtin_amdgcn_s_setprio(1); _Pragma("unroll") for (int m = 0; m < 4; ++m) _Pragma("unroll") for (int n = 0; n < 2; ++n) _Pragma("unroll") for (int k = 0; k < 2; ++k) \
;         acc[ai][bj][m][n] = __builtin_amdgcn_mfma_f32_16x16x32_bf16(Bt[n][k], At[m][k], acc[ai][bj][m][n], 0, 0, 0); __builtin_amdgcn_s_setprio(0); } while (0)
; #define PG8_WAIT_V(n) asm volatile("s_waitcnt vmcnt(" #n ")" ::: "memory")
; #define PG8_WAIT_L(n) asm volatile("s_waitcnt lgkmcnt(" #n ")" ::: "memory")
; #define PG8_BAR __builtin_amdgcn_s_barrier()
; #define PG8_SCHED __builtin_amdgcn_sched_barrier(0)
; template <class Epi, class Sched, bool ALIGN_EPI = false, bool SP2 = false, bool ACHUNK = false>
; __device__ __forceinline__ void gemm_phase(PG8_LAS unsigned char* lds, const Gemm g, const Sched& S, const Epi& E) {
;     ...
;             PG8_LDB(B0, 1, 0); PG8_LDB(B1, 1, 1); PG8_SCHED; PG8_LDA(At, 1, 0); PG8_STAGE(PG8_SA(0, 1), a2 + hstepA, voffA);
;             PG8_WAIT_V(8); PG8_WAIT_L(0); PG8_BAR; PG8_MMA(0, 0, At, B0); PG8_MMA(0, 1, At, B1); PG8_BAR; PG8_SCHED;
;             PG8_LDA(At, 1, 1); PG8_STAGE(PG8_SB(1, 0), b3, voffB); PG8_STAGE(PG8_SB(1, 1), b3 + hstepB, voffB); PG8_STAGE(PG8_SA(1, 0), a3, voffA);
;             PG8_WAIT_V(8); PG8_WAIT_L(0); PG8_BAR; PG8_MMA(1, 0, At, B0); PG8_MMA(1, 1, At, B1); PG8_BAR; PG8_SCHED;
.Lpe_join_353:
	s_add_i32 s43, 0, 0x18000
	v_add_u32_e32 v153, s43, v143
	s_add_i32 s44, 0, 0x1c000
	ds_read_b128 v[154:157], v153
	ds_read_b128 v[158:161], v153 offset:1024
	ds_read_b128 v[162:165], v153 offset:2048
	ds_read_b128 v[166:169], v153 offset:3072
	v_add_u32_e32 v153, s44, v143
	ds_read_b128 v[170:173], v153
	ds_read_b128 v[174:177], v153 offset:1024
	ds_read_b128 v[178:181], v153 offset:2048
	ds_read_b128 v[182:185], v153 offset:3072
	s_add_u32 s20, s20, s0
	s_addc_u32 s21, s21, s1
	s_mov_b32 m0, s27
	ds_read_b128 v[186:189], v152 offset:32768
	ds_read_b128 v[190:193], v152 offset:33792
	ds_read_b128 v[198:201], v152 offset:34816
	ds_read_b128 v[202:205], v152 offset:35840
	ds_read_b128 v[206:209], v152 offset:36864
	ds_read_b128 v[210:213], v152 offset:37888
	ds_read_b128 v[214:217], v152 offset:38912
	ds_read_b128 v[218:221], v152 offset:39936
	global_load_lds_dwordx4 v132, s[20:21]
	s_mov_b32 m0, s28
	s_nop 0
	global_load_lds_dwordx4 v134, s[20:21]
	s_waitcnt vmcnt(8)
	s_waitcnt lgkmcnt(0)
	s_barrier
	s_setprio 1
	v_mfma_f32_16x16x32_bf16 v[124:127], v[154:157], v[186:189], v[124:127]
	v_mfma_f32_16x16x32_bf16 v[128:131], v[162:165], v[186:189], v[128:131]
	v_mfma_f32_16x16x32_bf16 v[112:115], v[154:157], v[198:201], v[112:115]
	v_mfma_f32_16x16x32_bf16 v[108:111], v[162:165], v[198:201], v[108:111]
	v_mfma_f32_16x16x32_bf16 v[96:99], v[154:157], v[206:209], v[96:99]
	v_mfma_f32_16x16x32_bf16 v[92:95], v[162:165], v[206:209], v[92:95]
	v_mfma_f32_16x16x32_bf16 v[80:83], v[154:157], v[214:217], v[80:83]
	v_mfma_f32_16x16x32_bf16 v[76:79], v[162:165], v[214:217], v[76:79]
	v_mfma_f32_16x16x32_bf16 v[124:127], v[158:161], v[190:193], v[124:127]
	v_mfma_f32_16x16x32_bf16 v[128:131], v[166:169], v[190:193], v[128:131]
	v_mfma_f32_16x16x32_bf16 v[112:115], v[158:161], v[202:205], v[112:115]
	v_mfma_f32_16x16x32_bf16 v[108:111], v[166:169], v[202:205], v[108:111]
	v_mfma_f32_16x16x32_bf16 v[96:99], v[158:161], v[210:213], v[96:99]
	v_mfma_f32_16x16x32_bf16 v[92:95], v[166:169], v[210:213], v[92:95]
	v_mfma_f32_16x16x32_bf16 v[80:83], v[158:161], v[218:221], v[80:83]
	v_mfma_f32_16x16x32_bf16 v[76:79], v[166:169], v[218:221], v[76:79]
	s_setprio 0
	s_setprio 1
	v_mfma_f32_16x16x32_bf16 v[120:123], v[170:173], v[186:189], v[120:123]
	v_mfma_f32_16x16x32_bf16 v[116:119], v[178:181], v[186:189], v[116:119]
	v_mfma_f32_16x16x32_bf16 v[104:107], v[170:173], v[198:201], v[104:107]
	v_mfma_f32_16x16x32_bf16 v[100:103], v[178:181], v[198:201], v[100:103]
	v_mfma_f32_16x16x32_bf16 v[88:91], v[170:173], v[206:209], v[88:91]
	v_mfma_f32_16x16x32_bf16 v[84:87], v[178:181], v[206:209], v[84:87]
	v_mfma_f32_16x16x32_bf16 v[72:75], v[170:173], v[214:217], v[72:75]
	v_mfma_f32_16x16x32_bf16 v[68:71], v[178:181], v[214:217], v[68:71]
	v_mfma_f32_16x16x32_bf16 v[120:123], v[174:177], v[190:193], v[120:123]
	v_mfma_f32_16x16x32_bf16 v[116:119], v[182:185], v[190:193], v[116:119]
	v_mfma_f32_16x16x32_bf16 v[104:107], v[174:177], v[202:205], v[104:107]
	v_mfma_f32_16x16x32_bf16 v[100:103], v[182:185], v[202:205], v[100:103]
	v_mfma_f32_16x16x32_bf16 v[88:91], v[174:177], v[210:213], v[88:91]
	v_mfma_f32_16x16x32_bf16 v[84:87], v[182:185], v[210:213], v[84:87]
	v_mfma_f32_16x16x32_bf16 v[72:75], v[174:177], v[218:221], v[72:75]
	v_mfma_f32_16x16x32_bf16 v[68:71], v[182:185], v[218:221], v[68:71]
	s_setprio 0
	s_barrier
	s_add_u32 vcc_lo, vcc_lo, s10
	s_addc_u32 vcc_hi, vcc_hi, s11
	s_add_u32 s98, s98, s10
	s_addc_u32 s99, s99, s11
	s_sub_u32 s20, s20, s0
	s_subb_u32 s21, s21, s1
	s_add_u32 s20, s20, s10
	s_addc_u32 s21, s21, s11
	s_add_i32 m0, s43, s24
	ds_read_b128 v[186:189], v152 offset:49152
	ds_read_b128 v[190:193], v152 offset:50176
	ds_read_b128 v[198:201], v152 offset:51200
	ds_read_b128 v[202:205], v152 offset:52224
	ds_read_b128 v[206:209], v152 offset:53248
	ds_read_b128 v[210:213], v152 offset:54272
	ds_read_b128 v[214:217], v152 offset:55296
	ds_read_b128 v[218:221], v152 offset:56320
	global_load_lds_dwordx4 v2, s[98:99]
	s_add_i32 m0, m0, 0x2000
	s_nop 0
	global_load_lds_dwordx4 v136, s[98:99]
	s_add_i32 m0, s44, s24
	s_nop 0
	global_load_lds_dwordx4 v2, vcc
	s_add_i32 m0, m0, 0x2000
	s_nop 0
	global_load_lds_dwordx4 v136, vcc
	s_mov_b32 m0, s29
	s_nop 0
	global_load_lds_dwordx4 v132, s[20:21]
	s_mov_b32 m0, s30
	s_nop 0
	global_load_lds_dwordx4 v134, s[20:21]
	s_waitcnt vmcnt(8)
	s_waitcnt lgkmcnt(0)
	s_barrier
	s_setprio 1
	v_mfma_f32_16x16x32_bf16 v[64:67], v[154:157], v[186:189], v[64:67]
	v_mfma_f32_16x16x32_bf16 v[60:63], v[162:165], v[186:189], v[60:63]
	v_mfma_f32_16x16x32_bf16 v[48:51], v[154:157], v[198:201], v[48:51]
	v_mfma_f32_16x16x32_bf16 v[44:47], v[162:165], v[198:201], v[44:47]
	v_mfma_f32_16x16x32_bf16 v[32:35], v[154:157], v[206:209], v[32:35]
	v_mfma_f32_16x16x32_bf16 v[28:31], v[162:165], v[206:209], v[28:31]
	v_mfma_f32_16x16x32_bf16 v[16:19], v[154:157], v[214:217], v[16:19]
	v_mfma_f32_16x16x32_bf16 v[12:15], v[162:165], v[214:217], v[12:15]
	v_mfma_f32_16x16x32_bf16 v[64:67], v[158:161], v[190:193], v[64:67]
	v_mfma_f32_16x16x32_bf16 v[60:63], v[166:169], v[190:193], v[60:63]
	v_mfma_f32_16x16x32_bf16 v[48:51], v[158:161], v[202:205], v[48:51]
	v_mfma_f32_16x16x32_bf16 v[44:47], v[166:169], v[202:205], v[44:47]
	v_mfma_f32_16x16x32_bf16 v[32:35], v[158:161], v[210:213], v[32:35]
	v_mfma_f32_16x16x32_bf16 v[28:31], v[166:169], v[210:213], v[28:31]
	v_mfma_f32_16x16x32_bf16 v[16:19], v[158:161], v[218:221], v[16:19]
	v_mfma_f32_16x16x32_bf16 v[12:15], v[166:169], v[218:221], v[12:15]
	s_setprio 0
	s_setprio 1
	v_mfma_f32_16x16x32_bf16 v[56:59], v[170:173], v[186:189], v[56:59]
	v_mfma_f32_16x16x32_bf16 v[52:55], v[178:181], v[186:189], v[52:55]
	v_mfma_f32_16x16x32_bf16 v[40:43], v[170:173], v[198:201], v[40:43]
	v_mfma_f32_16x16x32_bf16 v[36:39], v[178:181], v[198:201], v[36:39]
	v_mfma_f32_16x16x32_bf16 v[24:27], v[170:173], v[206:209], v[24:27]
	v_mfma_f32_16x16x32_bf16 v[20:23], v[178:181], v[206:209], v[20:23]
	v_mfma_f32_16x16x32_bf16 v[8:11], v[170:173], v[214:217], v[8:11]
	v_mfma_f32_16x16x32_bf16 v[4:7], v[178:181], v[214:217], v[4:7]
	v_mfma_f32_16x16x32_bf16 v[56:59], v[174:177], v[190:193], v[56:59]
	v_mfma_f32_16x16x32_bf16 v[52:55], v[182:185], v[190:193], v[52:55]
	v_mfma_f32_16x16x32_bf16 v[40:43], v[174:177], v[202:205], v[40:43]
	v_mfma_f32_16x16x32_bf16 v[36:39], v[182:185], v[202:205], v[36:39]
	v_mfma_f32_16x16x32_bf16 v[24:27], v[174:177], v[210:213], v[24:27]
	v_mfma_f32_16x16x32_bf16 v[20:23], v[182:185], v[210:213], v[20:23]
	v_mfma_f32_16x16x32_bf16 v[8:11], v[174:177], v[218:221], v[8:11]
	v_mfma_f32_16x16x32_bf16 v[4:7], v[182:185], v[218:221], v[4:7]
	s_setprio 0
	s_barrier
	s_add_u32 s40, s40, 0x100
	s_addc_u32 s41, s41, 0
	s_add_u32 s18, s18, 0x100
	s_addc_u32 s19, s19, 0
	s_cmp_ge_i32 s42, s31
	s_mov_b32 s20, s42
	s_cbranch_scc0 .LBB0_353
	s_branch .LBB0_342

; #define PG8_STAGE(bufoff, gbase, voff) do { _Pragma("unroll") for (int _i = 0; _i < 2; ++_i) \
;         __builtin_amdgcn_global_load_lds((const unsigned*)((const char*)(gbase) + (voff)[_i]), (PG8_LAS unsigned*)(lds + (bufoff) + ldsw + _i * 8192), 16, 0, 0); } while (0)
; #define PG8_LDA(dst, b, h) do { _Pragma("unroll") for (int m = 0; m < 4; ++m) _Pragma("unroll") for (int k = 0; k < 2; ++k) dst[m][k] = *(const PG8_LAS bf16x8*)(lds + PG8_SA(b, h) + aoff + m * 2048 + k * 1024); } while (0)
; #define PG8_LDB(dst, b, h) do { _Pragma("unroll") for (int n = 0; n < 2; ++n) _Pragma("unroll") for (int k = 0; k < 2; ++k) dst[n][k] = *(const PG8_LAS bf16x8*)(lds + PG8_SB(b, h) + boff + n * 2048 + k * 1024); } while (0)
; #define PG8_WAIT_V(n) asm volatile("s_waitcnt vmcnt(" #n ")" ::: "memory")
; #define PG8_WAIT_L(n) asm volatile("s_waitcnt lgkmcnt(" #n ")" ::: "memory")
; template <class Epi, class Sched, bool ALIGN_EPI = false, bool SP2 = false, bool ACHUNK = false>
; __device__ __forceinline__ void gemm_phase(PG8_LAS unsigned char* lds, const Gemm g, const Sched& S, const Epi& E) {
;     ...
;         const bool has_next = S.next(ui + 1, nxt);
;         const char* nA = has_next ? (const char*)g.A + (size_t)nxt.pm * tstepA : cA; const char* nB = has_next ? (const char*)g.Bt + (size_t)nxt.pn * tstepB : cB;
;         for (int t = 0; t < nt; t += 2) {
;             const bool last = (t == nt - 2);
;             if constexpr (Epi::HAS_MID) { if (t == Epi::MID_T) E.mid(acc, cur, wr, wc, fr, fq, ShflDev{}); }
;             const char* a1 = cA + (size_t)(t + 1) * kstep;
;             const char* a2 = last ? nA : cA + (size_t)(t + 2) * kstep; const char* b2 = last ? nB : cB + (size_t)(t + 2) * kstep;
;             const char* a3 = a2 + kstep; const char* b3 = b2 + kstep;
;             if (last && has_next) S.a_ready(nxt);
;             if constexpr (SP2) {
;             PG8_LDB(B0, 0, 0); PG8_LDB(B1, 0, 1); PG8_SCHED; PG8_LDA(At, 0, 0); PG8_STAGE(PG8_SA(1, 1), a1 + hstepA, voffA);
;             PG8_WAIT_V(8); PG8_WAIT_L(0); PG8_BAR; PG8_MMA(0, 0, At, B0); PG8_MMA(0, 1, At, B1); PG8_BAR; PG8_SCHED;
;             PG8_LDA(At, 0, 1); PG8_STAGE(PG8_SB(0, 0), b2, voffB); PG8_STAGE(PG8_SB(0, 1), b2 + hstepB, voffB); PG8_STAGE(PG8_SA(0, 0), a2, voffA);
;             PG8_WAIT_V(8); PG8_WAIT_L(0); PG8_BAR; PG8_MMA(1, 0, At, B0); PG8_MMA(1, 1, At, B1); PG8_BAR; PG8_SCHED;
.LBB0_375:
	s_andn2_b64 vcc, exec, s[34:35]
	s_cbranch_vccnz .LBB0_379
	s_add_u32 s4, s4, 0x80
	s_addc_u32 s5, s5, 0
	s_add_u32 s8, s6, 0x100
	s_addc_u32 s9, s7, 0
	s_mov_b32 s6, 0
	s_add_i32 s48, s6, 2
	s_add_u32 s49, s4, 0x80
	s_addc_u32 s7, s5, 0
	s_add_i32 s52, 0, 0x10000
	s_cmp_eq_u32 s27, s6
	s_cselect_b32 s7, s1, s7
	s_cselect_b32 s6, s0, s49
	v_add_u32_e32 v2, s52, v175
	s_cselect_b32 s51, s43, s9
	s_cselect_b32 s50, s42, s8
	s_add_i32 s49, 0, 0x14000
	s_waitcnt lgkmcnt(0)
	ds_read_b128 v[146:149], v2
	ds_read_b128 v[150:153], v2 offset:1024
	ds_read_b128 v[154:157], v2 offset:2048
	ds_read_b128 v[158:161], v2 offset:3072
	v_add_u32_e32 v2, s49, v175
	ds_read_b128 v[162:165], v2
	ds_read_b128 v[166:169], v2 offset:1024
	ds_read_b128 v[170:173], v2 offset:2048
	ds_read_b128 v[180:183], v2 offset:3072
	s_add_i32 m0, s20, 0xc000
	ds_read_b128 v[184:187], v179
	ds_read_b128 v[188:191], v179 offset:1024
	ds_read_b128 v[198:201], v179 offset:2048
	ds_read_b128 v[202:205], v179 offset:3072
	ds_read_b128 v[206:209], v179 offset:4096
	ds_read_b128 v[210:213], v179 offset:5120
	ds_read_b128 v[214:217], v179 offset:6144
	ds_read_b128 v[218:221], v179 offset:7168
	global_load_lds_dwordx4 v142, s[4:5]
	s_add_i32 m0, s20, 0xe000
	s_nop 0
	global_load_lds_dwordx4 v144, s[4:5]
	s_waitcnt vmcnt(8)
	s_waitcnt lgkmcnt(0)
	s_barrier
	s_setprio 1
	v_mfma_f32_16x16x32_bf16 v[124:127], v[146:149], v[184:187], 0
	v_mfma_f32_16x16x32_bf16 v[116:119], v[154:157], v[184:187], 0
	v_mfma_f32_16x16x32_bf16 v[108:111], v[146:149], v[198:201], 0
	v_mfma_f32_16x16x32_bf16 v[100:103], v[154:157], v[198:201], 0
	v_mfma_f32_16x16x32_bf16 v[92:95], v[146:149], v[206:209], 0
	v_mfma_f32_16x16x32_bf16 v[84:87], v[154:157], v[206:209], 0
	v_mfma_f32_16x16x32_bf16 v[76:79], v[146:149], v[214:217], 0
	v_mfma_f32_16x16x32_bf16 v[68:71], v[154:157], v[214:217], 0
	v_mfma_f32_16x16x32_bf16 v[124:127], v[150:153], v[188:191], v[124:127]
	v_mfma_f32_16x16x32_bf16 v[116:119], v[158:161], v[188:191], v[116:119]
	v_mfma_f32_16x16x32_bf16 v[108:111], v[150:153], v[202:205], v[108:111]
	v_mfma_f32_16x16x32_bf16 v[100:103], v[158:161], v[202:205], v[100:103]
	v_mfma_f32_16x16x32_bf16 v[92:95], v[150:153], v[210:213], v[92:95]
	v_mfma_f32_16x16x32_bf16 v[84:87], v[158:161], v[210:213], v[84:87]
	v_mfma_f32_16x16x32_bf16 v[76:79], v[150:153], v[218:221], v[76:79]
	v_mfma_f32_16x16x32_bf16 v[68:71], v[158:161], v[218:221], v[68:71]
	s_setprio 0
	s_setprio 1
	v_mfma_f32_16x16x32_bf16 v[128:131], v[162:165], v[184:187], 0
	v_mfma_f32_16x16x32_bf16 v[120:123], v[170:173], v[184:187], 0
	v_mfma_f32_16x16x32_bf16 v[112:115], v[162:165], v[198:201], 0
	v_mfma_f32_16x16x32_bf16 v[104:107], v[170:173], v[198:201], 0
	v_mfma_f32_16x16x32_bf16 v[96:99], v[162:165], v[206:209], 0
	v_mfma_f32_16x16x32_bf16 v[88:91], v[170:173], v[206:209], 0
	v_mfma_f32_16x16x32_bf16 v[80:83], v[162:165], v[214:217], 0
	v_mfma_f32_16x16x32_bf16 v[72:75], v[170:173], v[214:217], 0
	v_mfma_f32_16x16x32_bf16 v[128:131], v[166:169], v[188:191], v[128:131]
	v_mfma_f32_16x16x32_bf16 v[120:123], v[180:183], v[188:191], v[120:123]
	v_mfma_f32_16x16x32_bf16 v[112:115], v[166:169], v[202:205], v[112:115]
	v_mfma_f32_16x16x32_bf16 v[104:107], v[180:183], v[202:205], v[104:107]
	v_mfma_f32_16x16x32_bf16 v[96:99], v[166:169], v[210:213], v[96:99]
	v_mfma_f32_16x16x32_bf16 v[88:91], v[180:183], v[210:213], v[88:91]
	v_mfma_f32_16x16x32_bf16 v[80:83], v[166:169], v[218:221], v[80:83]
	v_mfma_f32_16x16x32_bf16 v[72:75], v[180:183], v[218:221], v[72:75]
	s_setprio 0
	s_barrier
	s_add_i32 s52, s52, s13
	s_mov_b32 m0, s52
	ds_read_b128 v[184:187], v179 offset:16384
	ds_read_b128 v[188:191], v179 offset:17408
	ds_read_b128 v[198:201], v179 offset:18432
	ds_read_b128 v[202:205], v179 offset:19456
	ds_read_b128 v[206:209], v179 offset:20480
	ds_read_b128 v[210:213], v179 offset:21504
	ds_read_b128 v[214:217], v179 offset:22528
	ds_read_b128 v[218:221], v179 offset:23552
	global_load_lds_dwordx4 v134, s[50:51]
	s_add_i32 m0, s52, 0x2000
	s_add_i32 s49, s49, s13
	global_load_lds_dwordx4 v138, s[50:51]
	s_add_u32 s50, s50, s18
	s_addc_u32 s51, s51, s19
	s_mov_b64 vcc, s[50:51]
	s_sub_u32 s98, s50, s18
	s_subb_u32 s99, s51, s19
	s_mov_b32 m0, s49
	s_nop 0
	global_load_lds_dwordx4 v134, s[50:51]
	s_add_i32 m0, s49, 0x2000
	s_nop 0
	global_load_lds_dwordx4 v138, s[50:51]
	s_mov_b32 m0, s20
	s_nop 0
	global_load_lds_dwordx4 v132, s[6:7]
	s_mov_b32 m0, s21
	s_nop 0
	global_load_lds_dwordx4 v136, s[6:7]
	s_waitcnt vmcnt(8)
	s_waitcnt lgkmcnt(0)
	s_barrier
	s_setprio 1
	v_mfma_f32_16x16x32_bf16 v[60:63], v[146:149], v[184:187], 0
	v_mfma_f32_16x16x32_bf16 v[52:55], v[154:157], v[184:187], 0
	v_mfma_f32_16x16x32_bf16 v[44:47], v[146:149], v[198:201], 0
	v_mfma_f32_16x16x32_bf16 v[36:39], v[154:157], v[198:201], 0
	v_mfma_f32_16x16x32_bf16 v[28:31], v[146:149], v[206:209], 0
	v_mfma_f32_16x16x32_bf16 v[20:23], v[154:157], v[206:209], 0
	v_mfma_f32_16x16x32_bf16 v[12:15], v[146:149], v[214:217], 0
	v_mfma_f32_16x16x32_bf16 v[4:7], v[154:157], v[214:217], 0
	v_mfma_f32_16x16x32_bf16 v[60:63], v[150:153], v[188:191], v[60:63]
	v_mfma_f32_16x16x32_bf16 v[52:55], v[158:161], v[188:191], v[52:55]
	v_mfma_f32_16x16x32_bf16 v[44:47], v[150:153], v[202:205], v[44:47]
	v_mfma_f32_16x16x32_bf16 v[36:39], v[158:161], v[202:205], v[36:39]
	v_mfma_f32_16x16x32_bf16 v[28:31], v[150:153], v[210:213], v[28:31]
	v_mfma_f32_16x16x32_bf16 v[20:23], v[158:161], v[210:213], v[20:23]
	v_mfma_f32_16x16x32_bf16 v[12:15], v[150:153], v[218:221], v[12:15]
	v_mfma_f32_16x16x32_bf16 v[4:7], v[158:161], v[218:221], v[4:7]
	s_setprio 0
	s_setprio 1
	v_mfma_f32_16x16x32_bf16 v[64:67], v[162:165], v[184:187], 0
	v_mfma_f32_16x16x32_bf16 v[56:59], v[170:173], v[184:187], 0
	v_mfma_f32_16x16x32_bf16 v[48:51], v[162:165], v[198:201], 0
	v_mfma_f32_16x16x32_bf16 v[40:43], v[170:173], v[198:201], 0
	v_mfma_f32_16x16x32_bf16 v[32:35], v[162:165], v[206:209], 0
	v_mfma_f32_16x16x32_bf16 v[24:27], v[170:173], v[206:209], 0
	v_mfma_f32_16x16x32_bf16 v[16:19], v[162:165], v[214:217], 0
	v_mfma_f32_16x16x32_bf16 v[8:11], v[170:173], v[214:217], 0
	v_mfma_f32_16x16x32_bf16 v[64:67], v[166:169], v[188:191], v[64:67]
	v_mfma_f32_16x16x32_bf16 v[56:59], v[180:183], v[188:191], v[56:59]
	v_mfma_f32_16x16x32_bf16 v[48:51], v[166:169], v[202:205], v[48:51]
	v_mfma_f32_16x16x32_bf16 v[40:43], v[180:183], v[202:205], v[40:43]
	v_mfma_f32_16x16x32_bf16 v[32:35], v[166:169], v[210:213], v[32:35]
	v_mfma_f32_16x16x32_bf16 v[24:27], v[180:183], v[210:213], v[24:27]
	v_mfma_f32_16x16x32_bf16 v[16:19], v[166:169], v[218:221], v[16:19]
	v_mfma_f32_16x16x32_bf16 v[8:11], v[180:183], v[218:221], v[8:11]
	s_setprio 0
	s_barrier
	s_branch .Lpe_join_377

; #define PG8_STAGE(bufoff, gbase, voff) do { _Pragma("unroll") for (int _i = 0; _i < 2; ++_i) \
;         __builtin_amdgcn_global_load_lds((const unsigned*)((const char*)(gbase) + (voff)[_i]), (PG8_LAS unsigned*)(lds + (bufoff) + ldsw + _i * 8192), 16, 0, 0); } while (0)
; #define PG8_LDA(dst, b, h) do { _Pragma("unroll") for (int m = 0; m < 4; ++m) _Pragma("unroll") for (int k = 0; k < 2; ++k) dst[m][k] = *(const PG8_LAS bf16x8*)(lds + PG8_SA(b, h) + aoff + m * 2048 + k * 1024); } while (0)
; #define PG8_LDB(dst, b, h) do { _Pragma("unroll") for (int n = 0; n < 2; ++n) _Pragma("unroll") for (int k = 0; k < 2; ++k) dst[n][k] = *(const PG8_LAS bf16x8*)(lds + PG8_SB(b, h) + boff + n * 2048 + k * 1024); } while (0)
; #define PG8_MMA(ai, bj, At, Bt) do { __builtin_amdgcn_s_setprio(1); _Pragma("unroll") for (int m = 0; m < 4; ++m) _Pragma("unroll") for (int n = 0; n < 2; ++n) _Pragma("unroll") for (int k = 0; k < 2; ++k) \
;         acc[ai][bj][m][n] = __builtin_amdgcn_mfma_f32_16x16x32_bf16(Bt[n][k], At[m][k], acc[ai][bj][m][n], 0, 0, 0); __builtin_amdgcn_s_setprio(0); } while (0)
; #define PG8_WAIT_V(n) asm volatile("s_waitcnt vmcnt(" #n ")" ::: "memory")
; #define PG8_WAIT_L(n) asm volatile("s_waitcnt lgkmcnt(" #n ")" ::: "memory")
; #define PG8_BAR __builtin_amdgcn_s_barrier()
; #define PG8_SCHED __builtin_amdgcn_sched_barrier(0)
; template <class Epi, class Sched, bool ALIGN_EPI = false, bool SP2 = false, bool ACHUNK = false>
; __device__ __forceinline__ void gemm_phase(PG8_LAS unsigned char* lds, const Gemm g, const Sched& S, const Epi& E) {
;     ...
;             PG8_LDB(B0, 1, 0); PG8_LDB(B1, 1, 1); PG8_SCHED; PG8_LDA(At, 1, 0); PG8_STAGE(PG8_SA(0, 1), a2 + hstepA, voffA);
;             PG8_WAIT_V(8); PG8_WAIT_L(0); PG8_BAR; PG8_MMA(0, 0, At, B0); PG8_MMA(0, 1, At, B1); PG8_BAR; PG8_SCHED;
;             PG8_LDA(At, 1, 1); PG8_STAGE(PG8_SB(1, 0), b3, voffB); PG8_STAGE(PG8_SB(1, 1), b3 + hstepB, voffB); PG8_STAGE(PG8_SA(1, 0), a3, voffA);
;             PG8_WAIT_V(8); PG8_WAIT_L(0); PG8_BAR; PG8_MMA(1, 0, At, B0); PG8_MMA(1, 1, At, B1); PG8_BAR; PG8_SCHED;
.Lpe_join_377:
	s_add_i32 s49, 0, 0x18000
	v_add_u32_e32 v2, s49, v175
	s_add_i32 s50, 0, 0x1c000
	ds_read_b128 v[146:149], v2
	ds_read_b128 v[150:153], v2 offset:1024
	ds_read_b128 v[154:157], v2 offset:2048
	ds_read_b128 v[158:161], v2 offset:3072
	v_add_u32_e32 v2, s50, v175
	ds_read_b128 v[162:165], v2
	ds_read_b128 v[166:169], v2 offset:1024
	ds_read_b128 v[170:173], v2 offset:2048
	ds_read_b128 v[180:183], v2 offset:3072
	s_add_u32 s6, s6, s18
	s_addc_u32 s7, s7, s19
	s_mov_b32 m0, s22
	ds_read_b128 v[184:187], v179 offset:32768
	ds_read_b128 v[188:191], v179 offset:33792
	ds_read_b128 v[198:201], v179 offset:34816
	ds_read_b128 v[202:205], v179 offset:35840
	ds_read_b128 v[206:209], v179 offset:36864
	ds_read_b128 v[210:213], v179 offset:37888
	ds_read_b128 v[214:217], v179 offset:38912
	ds_read_b128 v[218:221], v179 offset:39936
	global_load_lds_dwordx4 v132, s[6:7]
	s_mov_b32 m0, s23
	s_nop 0
	global_load_lds_dwordx4 v136, s[6:7]
	s_waitcnt vmcnt(8)
	s_waitcnt lgkmcnt(0)
	s_barrier
	s_setprio 1
	v_mfma_f32_16x16x32_bf16 v[124:127], v[146:149], v[184:187], v[124:127]
	v_mfma_f32_16x16x32_bf16 v[116:119], v[154:157], v[184:187], v[116:119]
	v_mfma_f32_16x16x32_bf16 v[108:111], v[146:149], v[198:201], v[108:111]
	v_mfma_f32_16x16x32_bf16 v[100:103], v[154:157], v[198:201], v[100:103]
	v_mfma_f32_16x16x32_bf16 v[92:95], v[146:149], v[206:209], v[92:95]
	v_mfma_f32_16x16x32_bf16 v[84:87], v[154:157], v[206:209], v[84:87]
	v_mfma_f32_16x16x32_bf16 v[76:79], v[146:149], v[214:217], v[76:79]
	v_mfma_f32_16x16x32_bf16 v[68:71], v[154:157], v[214:217], v[68:71]
	v_mfma_f32_16x16x32_bf16 v[124:127], v[150:153], v[188:191], v[124:127]
	v_mfma_f32_16x16x32_bf16 v[116:119], v[158:161], v[188:191], v[116:119]
	v_mfma_f32_16x16x32_bf16 v[108:111], v[150:153], v[202:205], v[108:111]
	v_mfma_f32_16x16x32_bf16 v[100:103], v[158:161], v[202:205], v[100:103]
	v_mfma_f32_16x16x32_bf16 v[92:95], v[150:153], v[210:213], v[92:95]
	v_mfma_f32_16x16x32_bf16 v[84:87], v[158:161], v[210:213], v[84:87]
	v_mfma_f32_16x16x32_bf16 v[76:79], v[150:153], v[218:221], v[76:79]
	v_mfma_f32_16x16x32_bf16 v[68:71], v[158:161], v[218:221], v[68:71]
	s_setprio 0
	s_setprio 1
	v_mfma_f32_16x16x32_bf16 v[128:131], v[162:165], v[184:187], v[128:131]
	v_mfma_f32_16x16x32_bf16 v[120:123], v[170:173], v[184:187], v[120:123]
	v_mfma_f32_16x16x32_bf16 v[112:115], v[162:165], v[198:201], v[112:115]
	v_mfma_f32_16x16x32_bf16 v[104:107], v[170:173], v[198:201], v[104:107]
	v_mfma_f32_16x16x32_bf16 v[96:99], v[162:165], v[206:209], v[96:99]
	v_mfma_f32_16x16x32_bf16 v[88:91], v[170:173], v[206:209], v[88:91]
	v_mfma_f32_16x16x32_bf16 v[80:83], v[162:165], v[214:217], v[80:83]
	v_mfma_f32_16x16x32_bf16 v[72:75], v[170:173], v[214:217], v[72:75]
	v_mfma_f32_16x16x32_bf16 v[128:131], v[166:169], v[188:191], v[128:131]
	v_mfma_f32_16x16x32_bf16 v[120:123], v[180:183], v[188:191], v[120:123]
	v_mfma_f32_16x16x32_bf16 v[112:115], v[166:169], v[202:205], v[112:115]
	v_mfma_f32_16x16x32_bf16 v[104:107], v[180:183], v[202:205], v[104:107]
	v_mfma_f32_16x16x32_bf16 v[96:99], v[166:169], v[210:213], v[96:99]
	v_mfma_f32_16x16x32_bf16 v[88:91], v[180:183], v[210:213], v[88:91]
	v_mfma_f32_16x16x32_bf16 v[80:83], v[166:169], v[218:221], v[80:83]
	v_mfma_f32_16x16x32_bf16 v[72:75], v[180:183], v[218:221], v[72:75]
	s_setprio 0
	s_barrier
	s_add_u32 vcc_lo, vcc_lo, s10
	s_addc_u32 vcc_hi, vcc_hi, s11
	s_add_u32 s98, s98, s10
	s_addc_u32 s99, s99, s11
	s_sub_u32 s6, s6, s18
	s_subb_u32 s7, s7, s19
	s_add_u32 s6, s6, s10
	s_addc_u32 s7, s7, s11
	s_add_i32 m0, s49, s13
	ds_read_b128 v[184:187], v179 offset:49152
	ds_read_b128 v[188:191], v179 offset:50176
	ds_read_b128 v[198:201], v179 offset:51200
	ds_read_b128 v[202:205], v179 offset:52224
	ds_read_b128 v[206:209], v179 offset:53248
	ds_read_b128 v[210:213], v179 offset:54272
	ds_read_b128 v[214:217], v179 offset:55296
	ds_read_b128 v[218:221], v179 offset:56320
	global_load_lds_dwordx4 v134, s[98:99]
	s_add_i32 m0, m0, 0x2000
	s_nop 0
	global_load_lds_dwordx4 v138, s[98:99]
	s_add_i32 m0, s50, s13
	s_nop 0
	global_load_lds_dwordx4 v134, vcc
	s_add_i32 m0, m0, 0x2000
	s_nop 0
	global_load_lds_dwordx4 v138, vcc
	s_mov_b32 m0, s25
	s_nop 0
	global_load_lds_dwordx4 v132, s[6:7]
	s_mov_b32 m0, s26
	s_nop 0
	global_load_lds_dwordx4 v136, s[6:7]
	s_waitcnt vmcnt(8)
	s_waitcnt lgkmcnt(0)
	s_barrier
	s_setprio 1
	v_mfma_f32_16x16x32_bf16 v[60:63], v[146:149], v[184:187], v[60:63]
	v_mfma_f32_16x16x32_bf16 v[52:55], v[154:157], v[184:187], v[52:55]
	v_mfma_f32_16x16x32_bf16 v[44:47], v[146:149], v[198:201], v[44:47]
	v_mfma_f32_16x16x32_bf16 v[36:39], v[154:157], v[198:201], v[36:39]
	v_mfma_f32_16x16x32_bf16 v[28:31], v[146:149], v[206:209], v[28:31]
	v_mfma_f32_16x16x32_bf16 v[20:23], v[154:157], v[206:209], v[20:23]
	v_mfma_f32_16x16x32_bf16 v[12:15], v[146:149], v[214:217], v[12:15]
	v_mfma_f32_16x16x32_bf16 v[4:7], v[154:157], v[214:217], v[4:7]
	v_mfma_f32_16x16x32_bf16 v[60:63], v[150:153], v[188:191], v[60:63]
	v_mfma_f32_16x16x32_bf16 v[52:55], v[158:161], v[188:191], v[52:55]
	v_mfma_f32_16x16x32_bf16 v[44:47], v[150:153], v[202:205], v[44:47]
	v_mfma_f32_16x16x32_bf16 v[36:39], v[158:161], v[202:205], v[36:39]
	v_mfma_f32_16x16x32_bf16 v[28:31], v[150:153], v[210:213], v[28:31]
	v_mfma_f32_16x16x32_bf16 v[20:23], v[158:161], v[210:213], v[20:23]
	v_mfma_f32_16x16x32_bf16 v[12:15], v[150:153], v[218:221], v[12:15]
	v_mfma_f32_16x16x32_bf16 v[4:7], v[158:161], v[218:221], v[4:7]
	s_setprio 0
	s_setprio 1
	v_mfma_f32_16x16x32_bf16 v[64:67], v[162:165], v[184:187], v[64:67]
	v_mfma_f32_16x16x32_bf16 v[56:59], v[170:173], v[184:187], v[56:59]
	v_mfma_f32_16x16x32_bf16 v[48:51], v[162:165], v[198:201], v[48:51]
	v_mfma_f32_16x16x32_bf16 v[40:43], v[170:173], v[198:201], v[40:43]
	v_mfma_f32_16x16x32_bf16 v[32:35], v[162:165], v[206:209], v[32:35]
	v_mfma_f32_16x16x32_bf16 v[24:27], v[170:173], v[206:209], v[24:27]
	v_mfma_f32_16x16x32_bf16 v[16:19], v[162:165], v[214:217], v[16:19]
	v_mfma_f32_16x16x32_bf16 v[8:11], v[170:173], v[214:217], v[8:11]
	v_mfma_f32_16x16x32_bf16 v[64:67], v[166:169], v[188:191], v[64:67]
	v_mfma_f32_16x16x32_bf16 v[56:59], v[180:183], v[188:191], v[56:59]
	v_mfma_f32_16x16x32_bf16 v[48:51], v[166:169], v[202:205], v[48:51]
	v_mfma_f32_16x16x32_bf16 v[40:43], v[180:183], v[202:205], v[40:43]
	v_mfma_f32_16x16x32_bf16 v[32:35], v[166:169], v[210:213], v[32:35]
	v_mfma_f32_16x16x32_bf16 v[24:27], v[180:183], v[210:213], v[24:27]
	v_mfma_f32_16x16x32_bf16 v[16:19], v[166:169], v[218:221], v[16:19]
	v_mfma_f32_16x16x32_bf16 v[8:11], v[180:183], v[218:221], v[8:11]
	s_setprio 0
	s_barrier
	s_add_u32 s4, s4, 0x100
	s_addc_u32 s5, s5, 0
	s_add_u32 s8, s8, 0x100
	s_addc_u32 s9, s9, 0
	s_cmp_ge_i32 s48, s24
	s_mov_b32 s6, s48
	s_cbranch_scc0 .LBB0_377
	v_readlane_b32 s52, v254, 27
	v_readlane_b32 s53, v254, 28
	s_mov_b32 s50, s94

; #define PG8_STAGE(bufoff, gbase, voff) do { _Pragma("unroll") for (int _i = 0; _i < 2; ++_i) \
;         __builtin_amdgcn_global_load_lds((const unsigned*)((const char*)(gbase) + (voff)[_i]), (PG8_LAS unsigned*)(lds + (bufoff) + ldsw + _i * 8192), 16, 0, 0); } while (0)
; #define PG8_LDA(dst, b, h) do { _Pragma("unroll") for (int m = 0; m < 4; ++m) _Pragma("unroll") for (int k = 0; k < 2; ++k) dst[m][k] = *(const PG8_LAS bf16x8*)(lds + PG8_SA(b, h) + aoff + m * 2048 + k * 1024); } while (0)
; #define PG8_LDB(dst, b, h) do { _Pragma("unroll") for (int n = 0; n < 2; ++n) _Pragma("unroll") for (int k = 0; k < 2; ++k) dst[n][k] = *(const PG8_LAS bf16x8*)(lds + PG8_SB(b, h) + boff + n * 2048 + k * 1024); } while (0)
; #define PG8_WAIT_V(n) asm volatile("s_waitcnt vmcnt(" #n ")" ::: "memory")
; #define PG8_WAIT_L(n) asm volatile("s_waitcnt lgkmcnt(" #n ")" ::: "memory")
; template <class Epi, class Sched, bool ALIGN_EPI = false, bool SP2 = false, bool ACHUNK = false>
; __device__ __forceinline__ void gemm_phase(PG8_LAS unsigned char* lds, const Gemm g, const Sched& S, const Epi& E) {
;     ...
;         const bool has_next = S.next(ui + 1, nxt);
;         const char* nA = has_next ? (const char*)g.A + (size_t)nxt.pm * tstepA : cA; const char* nB = has_next ? (const char*)g.Bt + (size_t)nxt.pn * tstepB : cB;
;         for (int t = 0; t < nt; t += 2) {
;             const bool last = (t == nt - 2);
;             if constexpr (Epi::HAS_MID) { if (t == Epi::MID_T) E.mid(acc, cur, wr, wc, fr, fq, ShflDev{}); }
;             const char* a1 = cA + (size_t)(t + 1) * kstep;
;             const char* a2 = last ? nA : cA + (size_t)(t + 2) * kstep; const char* b2 = last ? nB : cB + (size_t)(t + 2) * kstep;
;             const char* a3 = a2 + kstep; const char* b3 = b2 + kstep;
;             if (last && has_next) S.a_ready(nxt);
;             if constexpr (SP2) {
;             PG8_LDB(B0, 0, 0); PG8_LDB(B1, 0, 1); PG8_SCHED; PG8_LDA(At, 0, 0); PG8_STAGE(PG8_SA(1, 1), a1 + hstepA, voffA);
;             PG8_WAIT_V(8); PG8_WAIT_L(0); PG8_BAR; PG8_MMA(0, 0, At, B0); PG8_MMA(0, 1, At, B1); PG8_BAR; PG8_SCHED;
;             PG8_LDA(At, 0, 1); PG8_STAGE(PG8_SB(0, 0), b2, voffB); PG8_STAGE(PG8_SB(0, 1), b2 + hstepB, voffB); PG8_STAGE(PG8_SA(0, 0), a2, voffA);
;             PG8_WAIT_V(8); PG8_WAIT_L(0); PG8_BAR; PG8_MMA(1, 0, At, B0); PG8_MMA(1, 1, At, B1); PG8_BAR; PG8_SCHED;
.LBB0_429:
	s_andn2_b64 vcc, exec, s[54:55]
	s_nop 0
	s_cbranch_vccnz .LBB0_432
	s_add_u32 s0, s6, 0x80
	s_addc_u32 s1, s7, 0
	s_add_u32 s6, s4, 0x100
	s_addc_u32 s7, s5, 0
	s_mov_b32 s4, 0
	s_add_i32 s8, s4, 2
	s_add_u32 s9, s0, 0x80
	s_addc_u32 s5, s1, 0
	s_add_i32 s15, 0, 0x10000
	s_cmp_eq_u32 s81, s4
	s_cselect_b32 s5, s31, s5
	s_cselect_b32 s4, s30, s9
	s_cselect_b32 s17, s93, s7
	s_cselect_b32 s16, s92, s6
	s_cbranch_scc0 .Lnl_pl_pe
	s_cmpk_lg_u32 s87, 0x100
	s_cbranch_scc1 .Lnl_pl_pe
	v_mov_b32_e32 v2, 0
	v_mov_b32_e32 v168, 0
	v_mov_b32_e32 v164, 0
	v_mov_b32_e32 v166, 0
.Lnl_pl_pe:
	s_add_i32 s9, 0, 0x14000
	v_add_u32_e32 v144, s15, v221
	v_add_u32_e32 v160, s9, v221
	ds_read_b128 v[132:135], v144
	ds_read_b128 v[136:139], v144 offset:1024
	ds_read_b128 v[140:143], v144 offset:2048
	ds_read_b128 v[144:147], v144 offset:3072
	ds_read_b128 v[148:151], v160
	ds_read_b128 v[152:155], v160 offset:1024
	ds_read_b128 v[156:159], v160 offset:2048
	ds_read_b128 v[160:163], v160 offset:3072
	s_add_i32 m0, s27, 0xc000
	ds_read_b128 v[178:181], v223
	ds_read_b128 v[182:185], v223 offset:1024
	ds_read_b128 v[186:189], v223 offset:2048
	ds_read_b128 v[190:193], v223 offset:3072
	ds_read_b128 v[198:201], v223 offset:4096
	ds_read_b128 v[202:205], v223 offset:5120
	ds_read_b128 v[206:209], v223 offset:6144
	ds_read_b128 v[210:213], v223 offset:7168
	global_load_lds_dwordx4 v174, s[0:1]
	s_add_i32 m0, s27, 0xe000
	s_nop 0
	global_load_lds_dwordx4 v176, s[0:1]
	s_waitcnt vmcnt(8)
	s_waitcnt lgkmcnt(0)
	s_barrier
	s_setprio 1
	v_mfma_f32_16x16x32_bf16 v[128:131], v[132:135], v[178:181], 0
	v_mfma_f32_16x16x32_bf16 v[124:127], v[140:143], v[178:181], 0
	v_mfma_f32_16x16x32_bf16 v[112:115], v[132:135], v[186:189], 0
	v_mfma_f32_16x16x32_bf16 v[108:111], v[140:143], v[186:189], 0
	v_mfma_f32_16x16x32_bf16 v[96:99], v[132:135], v[198:201], 0
	v_mfma_f32_16x16x32_bf16 v[92:95], v[140:143], v[198:201], 0
	v_mfma_f32_16x16x32_bf16 v[80:83], v[132:135], v[206:209], 0
	v_mfma_f32_16x16x32_bf16 v[76:79], v[140:143], v[206:209], 0
	v_mfma_f32_16x16x32_bf16 v[128:131], v[136:139], v[182:185], v[128:131]
	v_mfma_f32_16x16x32_bf16 v[124:127], v[144:147], v[182:185], v[124:127]
	v_mfma_f32_16x16x32_bf16 v[112:115], v[136:139], v[190:193], v[112:115]
	v_mfma_f32_16x16x32_bf16 v[108:111], v[144:147], v[190:193], v[108:111]
	v_mfma_f32_16x16x32_bf16 v[96:99], v[136:139], v[202:205], v[96:99]
	v_mfma_f32_16x16x32_bf16 v[92:95], v[144:147], v[202:205], v[92:95]
	v_mfma_f32_16x16x32_bf16 v[80:83], v[136:139], v[210:213], v[80:83]
	v_mfma_f32_16x16x32_bf16 v[76:79], v[144:147], v[210:213], v[76:79]
	s_setprio 0
	s_setprio 1
	v_mfma_f32_16x16x32_bf16 v[120:123], v[148:151], v[178:181], 0
	v_mfma_f32_16x16x32_bf16 v[116:119], v[156:159], v[178:181], 0
	v_mfma_f32_16x16x32_bf16 v[104:107], v[148:151], v[186:189], 0
	v_mfma_f32_16x16x32_bf16 v[100:103], v[156:159], v[186:189], 0
	v_mfma_f32_16x16x32_bf16 v[88:91], v[148:151], v[198:201], 0
	v_mfma_f32_16x16x32_bf16 v[84:87], v[156:159], v[198:201], 0
	v_mfma_f32_16x16x32_bf16 v[72:75], v[148:151], v[206:209], 0
	v_mfma_f32_16x16x32_bf16 v[68:71], v[156:159], v[206:209], 0
	v_mfma_f32_16x16x32_bf16 v[120:123], v[152:155], v[182:185], v[120:123]
	v_mfma_f32_16x16x32_bf16 v[116:119], v[160:163], v[182:185], v[116:119]
	v_mfma_f32_16x16x32_bf16 v[104:107], v[152:155], v[190:193], v[104:107]
	v_mfma_f32_16x16x32_bf16 v[100:103], v[160:163], v[190:193], v[100:103]
	v_mfma_f32_16x16x32_bf16 v[88:91], v[152:155], v[202:205], v[88:91]
	v_mfma_f32_16x16x32_bf16 v[84:87], v[160:163], v[202:205], v[84:87]
	v_mfma_f32_16x16x32_bf16 v[72:75], v[152:155], v[210:213], v[72:75]
	v_mfma_f32_16x16x32_bf16 v[68:71], v[160:163], v[210:213], v[68:71]
	s_setprio 0
	s_barrier
	s_add_i32 s15, s15, s26
	s_mov_b32 m0, s15
	ds_read_b128 v[178:181], v223 offset:16384
	ds_read_b128 v[182:185], v223 offset:17408
	ds_read_b128 v[186:189], v223 offset:18432
	ds_read_b128 v[190:193], v223 offset:19456
	ds_read_b128 v[198:201], v223 offset:20480
	ds_read_b128 v[202:205], v223 offset:21504
	ds_read_b128 v[206:209], v223 offset:22528
	ds_read_b128 v[210:213], v223 offset:23552
	global_load_lds_dwordx4 v2, s[16:17]
	s_add_i32 m0, s15, 0x2000
	s_add_i32 s9, s9, s26
	global_load_lds_dwordx4 v168, s[16:17]
	s_add_u32 s16, s16, s18
	s_addc_u32 s17, s17, s19
	s_mov_b64 vcc, s[16:17]
	s_sub_u32 s98, s16, s18
	s_subb_u32 s99, s17, s19
	s_mov_b32 m0, s9
	s_nop 0
	global_load_lds_dwordx4 v2, s[16:17]
	s_add_i32 m0, s9, 0x2000
	s_nop 0
	global_load_lds_dwordx4 v168, s[16:17]
	s_mov_b32 m0, s27
	s_nop 0
	global_load_lds_dwordx4 v164, s[4:5]
	s_mov_b32 m0, s36
	s_nop 0
	global_load_lds_dwordx4 v166, s[4:5]
	s_waitcnt vmcnt(8)
	s_waitcnt lgkmcnt(0)
	s_barrier
	s_setprio 1
	v_mfma_f32_16x16x32_bf16 v[64:67], v[132:135], v[178:181], 0
	v_mfma_f32_16x16x32_bf16 v[60:63], v[140:143], v[178:181], 0
	v_mfma_f32_16x16x32_bf16 v[48:51], v[132:135], v[186:189], 0
	v_mfma_f32_16x16x32_bf16 v[44:47], v[140:143], v[186:189], 0
	v_mfma_f32_16x16x32_bf16 v[32:35], v[132:135], v[198:201], 0
	v_mfma_f32_16x16x32_bf16 v[28:31], v[140:143], v[198:201], 0
	v_mfma_f32_16x16x32_bf16 v[16:19], v[132:135], v[206:209], 0
	v_mfma_f32_16x16x32_bf16 v[12:15], v[140:143], v[206:209], 0
	v_mfma_f32_16x16x32_bf16 v[64:67], v[136:139], v[182:185], v[64:67]
	v_mfma_f32_16x16x32_bf16 v[60:63], v[144:147], v[182:185], v[60:63]
	v_mfma_f32_16x16x32_bf16 v[48:51], v[136:139], v[190:193], v[48:51]
	v_mfma_f32_16x16x32_bf16 v[44:47], v[144:147], v[190:193], v[44:47]
	v_mfma_f32_16x16x32_bf16 v[32:35], v[136:139], v[202:205], v[32:35]
	v_mfma_f32_16x16x32_bf16 v[28:31], v[144:147], v[202:205], v[28:31]
	v_mfma_f32_16x16x32_bf16 v[16:19], v[136:139], v[210:213], v[16:19]
	v_mfma_f32_16x16x32_bf16 v[12:15], v[144:147], v[210:213], v[12:15]
	s_setprio 0
	s_setprio 1
	v_mfma_f32_16x16x32_bf16 v[56:59], v[148:151], v[178:181], 0
	v_mfma_f32_16x16x32_bf16 v[52:55], v[156:159], v[178:181], 0
	v_mfma_f32_16x16x32_bf16 v[40:43], v[148:151], v[186:189], 0
	v_mfma_f32_16x16x32_bf16 v[36:39], v[156:159], v[186:189], 0
	v_mfma_f32_16x16x32_bf16 v[24:27], v[148:151], v[198:201], 0
	v_mfma_f32_16x16x32_bf16 v[20:23], v[156:159], v[198:201], 0
	v_mfma_f32_16x16x32_bf16 v[8:11], v[148:151], v[206:209], 0
	v_mfma_f32_16x16x32_bf16 v[4:7], v[156:159], v[206:209], 0
	v_mfma_f32_16x16x32_bf16 v[56:59], v[152:155], v[182:185], v[56:59]
	v_mfma_f32_16x16x32_bf16 v[52:55], v[160:163], v[182:185], v[52:55]
	v_mfma_f32_16x16x32_bf16 v[40:43], v[152:155], v[190:193], v[40:43]
	v_mfma_f32_16x16x32_bf16 v[36:39], v[160:163], v[190:193], v[36:39]
	v_mfma_f32_16x16x32_bf16 v[24:27], v[152:155], v[202:205], v[24:27]
	v_mfma_f32_16x16x32_bf16 v[20:23], v[160:163], v[202:205], v[20:23]
	v_mfma_f32_16x16x32_bf16 v[8:11], v[152:155], v[210:213], v[8:11]
	v_mfma_f32_16x16x32_bf16 v[4:7], v[160:163], v[210:213], v[4:7]
	s_setprio 0
	s_barrier
	s_branch .Lpe_join_431

; #define PG8_STAGE(bufoff, gbase, voff) do { _Pragma("unroll") for (int _i = 0; _i < 2; ++_i) \
;         __builtin_amdgcn_global_load_lds((const unsigned*)((const char*)(gbase) + (voff)[_i]), (PG8_LAS unsigned*)(lds + (bufoff) + ldsw + _i * 8192), 16, 0, 0); } while (0)
; #define PG8_LDA(dst, b, h) do { _Pragma("unroll") for (int m = 0; m < 4; ++m) _Pragma("unroll") for (int k = 0; k < 2; ++k) dst[m][k] = *(const PG8_LAS bf16x8*)(lds + PG8_SA(b, h) + aoff + m * 2048 + k * 1024); } while (0)
; #define PG8_LDB(dst, b, h) do { _Pragma("unroll") for (int n = 0; n < 2; ++n) _Pragma("unroll") for (int k = 0; k < 2; ++k) dst[n][k] = *(const PG8_LAS bf16x8*)(lds + PG8_SB(b, h) + boff + n * 2048 + k * 1024); } while (0)
; #define PG8_MMA(ai, bj, At, Bt) do { __builtin_amdgcn_s_setprio(1); _Pragma("unroll") for (int m = 0; m < 4; ++m) _Pragma("unroll") for (int n = 0; n < 2; ++n) _Pragma("unroll") for (int k = 0; k < 2; ++k) \
;         acc[ai][bj][m][n] = __builtin_amdgcn_mfma_f32_16x16x32_bf16(Bt[n][k], At[m][k], acc[ai][bj][m][n], 0, 0, 0); __builtin_amdgcn_s_setprio(0); } while (0)
; #define PG8_WAIT_V(n) asm volatile("s_waitcnt vmcnt(" #n ")" ::: "memory")
; #define PG8_WAIT_L(n) asm volatile("s_waitcnt lgkmcnt(" #n ")" ::: "memory")
; #define PG8_BAR __builtin_amdgcn_s_barrier()
; #define PG8_SCHED __builtin_amdgcn_sched_barrier(0)
; template <class Epi, class Sched, bool ALIGN_EPI = false, bool SP2 = false, bool ACHUNK = false>
; __device__ __forceinline__ void gemm_phase(PG8_LAS unsigned char* lds, const Gemm g, const Sched& S, const Epi& E) {
;     ...
;             PG8_LDB(B0, 1, 0); PG8_LDB(B1, 1, 1); PG8_SCHED; PG8_LDA(At, 1, 0); PG8_STAGE(PG8_SA(0, 1), a2 + hstepA, voffA);
;             PG8_WAIT_V(8); PG8_WAIT_L(0); PG8_BAR; PG8_MMA(0, 0, At, B0); PG8_MMA(0, 1, At, B1); PG8_BAR; PG8_SCHED;
;             PG8_LDA(At, 1, 1); PG8_STAGE(PG8_SB(1, 0), b3, voffB); PG8_STAGE(PG8_SB(1, 1), b3 + hstepB, voffB); PG8_STAGE(PG8_SA(1, 0), a3, voffA);
;             PG8_WAIT_V(8); PG8_WAIT_L(0); PG8_BAR; PG8_MMA(1, 0, At, B0); PG8_MMA(1, 1, At, B1); PG8_BAR; PG8_SCHED;
.Lpe_join_431:
	s_add_i32 s9, 0, 0x18000
	s_add_i32 s15, 0, 0x1c000
	v_add_u32_e32 v144, s9, v221
	v_add_u32_e32 v160, s15, v221
	ds_read_b128 v[132:135], v144
	ds_read_b128 v[136:139], v144 offset:1024
	ds_read_b128 v[140:143], v144 offset:2048
	ds_read_b128 v[144:147], v144 offset:3072
	ds_read_b128 v[148:151], v160
	ds_read_b128 v[152:155], v160 offset:1024
	ds_read_b128 v[156:159], v160 offset:2048
	ds_read_b128 v[160:163], v160 offset:3072
	s_add_u32 s4, s4, s18
	s_addc_u32 s5, s5, s19
	s_mov_b32 m0, s37
	ds_read_b128 v[178:181], v223 offset:32768
	ds_read_b128 v[182:185], v223 offset:33792
	ds_read_b128 v[186:189], v223 offset:34816
	ds_read_b128 v[190:193], v223 offset:35840
	ds_read_b128 v[198:201], v223 offset:36864
	ds_read_b128 v[202:205], v223 offset:37888
	ds_read_b128 v[206:209], v223 offset:38912
	ds_read_b128 v[210:213], v223 offset:39936
	global_load_lds_dwordx4 v164, s[4:5]
	s_mov_b32 m0, s76
	s_nop 0
	global_load_lds_dwordx4 v166, s[4:5]
	s_waitcnt vmcnt(8)
	s_waitcnt lgkmcnt(0)
	s_barrier
	s_setprio 1
	v_mfma_f32_16x16x32_bf16 v[128:131], v[132:135], v[178:181], v[128:131]
	v_mfma_f32_16x16x32_bf16 v[124:127], v[140:143], v[178:181], v[124:127]
	v_mfma_f32_16x16x32_bf16 v[112:115], v[132:135], v[186:189], v[112:115]
	v_mfma_f32_16x16x32_bf16 v[108:111], v[140:143], v[186:189], v[108:111]
	v_mfma_f32_16x16x32_bf16 v[96:99], v[132:135], v[198:201], v[96:99]
	v_mfma_f32_16x16x32_bf16 v[92:95], v[140:143], v[198:201], v[92:95]
	v_mfma_f32_16x16x32_bf16 v[80:83], v[132:135], v[206:209], v[80:83]
	v_mfma_f32_16x16x32_bf16 v[76:79], v[140:143], v[206:209], v[76:79]
	v_mfma_f32_16x16x32_bf16 v[128:131], v[136:139], v[182:185], v[128:131]
	v_mfma_f32_16x16x32_bf16 v[124:127], v[144:147], v[182:185], v[124:127]
	v_mfma_f32_16x16x32_bf16 v[112:115], v[136:139], v[190:193], v[112:115]
	v_mfma_f32_16x16x32_bf16 v[108:111], v[144:147], v[190:193], v[108:111]
	v_mfma_f32_16x16x32_bf16 v[96:99], v[136:139], v[202:205], v[96:99]
	v_mfma_f32_16x16x32_bf16 v[92:95], v[144:147], v[202:205], v[92:95]
	v_mfma_f32_16x16x32_bf16 v[80:83], v[136:139], v[210:213], v[80:83]
	v_mfma_f32_16x16x32_bf16 v[76:79], v[144:147], v[210:213], v[76:79]
	s_setprio 0
	s_setprio 1
	v_mfma_f32_16x16x32_bf16 v[120:123], v[148:151], v[178:181], v[120:123]
	v_mfma_f32_16x16x32_bf16 v[116:119], v[156:159], v[178:181], v[116:119]
	v_mfma_f32_16x16x32_bf16 v[104:107], v[148:151], v[186:189], v[104:107]
	v_mfma_f32_16x16x32_bf16 v[100:103], v[156:159], v[186:189], v[100:103]
	v_mfma_f32_16x16x32_bf16 v[88:91], v[148:151], v[198:201], v[88:91]
	v_mfma_f32_16x16x32_bf16 v[84:87], v[156:159], v[198:201], v[84:87]
	v_mfma_f32_16x16x32_bf16 v[72:75], v[148:151], v[206:209], v[72:75]
	v_mfma_f32_16x16x32_bf16 v[68:71], v[156:159], v[206:209], v[68:71]
	v_mfma_f32_16x16x32_bf16 v[120:123], v[152:155], v[182:185], v[120:123]
	v_mfma_f32_16x16x32_bf16 v[116:119], v[160:163], v[182:185], v[116:119]
	v_mfma_f32_16x16x32_bf16 v[104:107], v[152:155], v[190:193], v[104:107]
	v_mfma_f32_16x16x32_bf16 v[100:103], v[160:163], v[190:193], v[100:103]
	v_mfma_f32_16x16x32_bf16 v[88:91], v[152:155], v[202:205], v[88:91]
	v_mfma_f32_16x16x32_bf16 v[84:87], v[160:163], v[202:205], v[84:87]
	v_mfma_f32_16x16x32_bf16 v[72:75], v[152:155], v[210:213], v[72:75]
	v_mfma_f32_16x16x32_bf16 v[68:71], v[160:163], v[210:213], v[68:71]
	s_setprio 0
	s_barrier
	s_add_u32 vcc_lo, vcc_lo, s10
	s_addc_u32 vcc_hi, vcc_hi, s11
	s_add_u32 s98, s98, s10
	s_addc_u32 s99, s99, s11
	s_sub_u32 s4, s4, s18
	s_subb_u32 s5, s5, s19
	s_add_u32 s4, s4, s10
	s_addc_u32 s5, s5, s11
	s_add_i32 m0, s9, s26
	ds_read_b128 v[178:181], v223 offset:49152
	ds_read_b128 v[182:185], v223 offset:50176
	ds_read_b128 v[186:189], v223 offset:51200
	ds_read_b128 v[190:193], v223 offset:52224
	ds_read_b128 v[198:201], v223 offset:53248
	ds_read_b128 v[202:205], v223 offset:54272
	ds_read_b128 v[206:209], v223 offset:55296
	ds_read_b128 v[210:213], v223 offset:56320
	global_load_lds_dwordx4 v2, s[98:99]
	s_add_i32 m0, m0, 0x2000
	s_nop 0
	global_load_lds_dwordx4 v168, s[98:99]
	s_add_i32 m0, s15, s26
	s_nop 0
	global_load_lds_dwordx4 v2, vcc
	s_add_i32 m0, m0, 0x2000
	s_nop 0
	global_load_lds_dwordx4 v168, vcc
	s_mov_b32 m0, s77
	s_nop 0
	global_load_lds_dwordx4 v164, s[4:5]
	s_mov_b32 m0, s78
	s_nop 0
	global_load_lds_dwordx4 v166, s[4:5]
	s_waitcnt vmcnt(8)
	s_waitcnt lgkmcnt(0)
	s_barrier
	s_setprio 1
	v_mfma_f32_16x16x32_bf16 v[64:67], v[132:135], v[178:181], v[64:67]
	v_mfma_f32_16x16x32_bf16 v[60:63], v[140:143], v[178:181], v[60:63]
	v_mfma_f32_16x16x32_bf16 v[48:51], v[132:135], v[186:189], v[48:51]
	v_mfma_f32_16x16x32_bf16 v[44:47], v[140:143], v[186:189], v[44:47]
	v_mfma_f32_16x16x32_bf16 v[32:35], v[132:135], v[198:201], v[32:35]
	v_mfma_f32_16x16x32_bf16 v[28:31], v[140:143], v[198:201], v[28:31]
	v_mfma_f32_16x16x32_bf16 v[16:19], v[132:135], v[206:209], v[16:19]
	v_mfma_f32_16x16x32_bf16 v[12:15], v[140:143], v[206:209], v[12:15]
	v_mfma_f32_16x16x32_bf16 v[64:67], v[136:139], v[182:185], v[64:67]
	v_mfma_f32_16x16x32_bf16 v[60:63], v[144:147], v[182:185], v[60:63]
	v_mfma_f32_16x16x32_bf16 v[48:51], v[136:139], v[190:193], v[48:51]
	v_mfma_f32_16x16x32_bf16 v[44:47], v[144:147], v[190:193], v[44:47]
	v_mfma_f32_16x16x32_bf16 v[32:35], v[136:139], v[202:205], v[32:35]
	v_mfma_f32_16x16x32_bf16 v[28:31], v[144:147], v[202:205], v[28:31]
	v_mfma_f32_16x16x32_bf16 v[16:19], v[136:139], v[210:213], v[16:19]
	v_mfma_f32_16x16x32_bf16 v[12:15], v[144:147], v[210:213], v[12:15]
	s_setprio 0
	s_setprio 1
	v_mfma_f32_16x16x32_bf16 v[56:59], v[148:151], v[178:181], v[56:59]
	v_mfma_f32_16x16x32_bf16 v[52:55], v[156:159], v[178:181], v[52:55]
	v_mfma_f32_16x16x32_bf16 v[40:43], v[148:151], v[186:189], v[40:43]
	v_mfma_f32_16x16x32_bf16 v[36:39], v[156:159], v[186:189], v[36:39]
	v_mfma_f32_16x16x32_bf16 v[24:27], v[148:151], v[198:201], v[24:27]
	v_mfma_f32_16x16x32_bf16 v[20:23], v[156:159], v[198:201], v[20:23]
	v_mfma_f32_16x16x32_bf16 v[8:11], v[148:151], v[206:209], v[8:11]
	v_mfma_f32_16x16x32_bf16 v[4:7], v[156:159], v[206:209], v[4:7]
	v_mfma_f32_16x16x32_bf16 v[56:59], v[152:155], v[182:185], v[56:59]
	v_mfma_f32_16x16x32_bf16 v[52:55], v[160:163], v[182:185], v[52:55]
	v_mfma_f32_16x16x32_bf16 v[40:43], v[152:155], v[190:193], v[40:43]
	v_mfma_f32_16x16x32_bf16 v[36:39], v[160:163], v[190:193], v[36:39]
	v_mfma_f32_16x16x32_bf16 v[24:27], v[152:155], v[202:205], v[24:27]
	v_mfma_f32_16x16x32_bf16 v[20:23], v[160:163], v[202:205], v[20:23]
	v_mfma_f32_16x16x32_bf16 v[8:11], v[152:155], v[210:213], v[8:11]
	v_mfma_f32_16x16x32_bf16 v[4:7], v[160:163], v[210:213], v[4:7]
	s_setprio 0
	s_barrier
	s_add_u32 s0, s0, 0x100
	s_addc_u32 s1, s1, 0
	s_add_u32 s6, s6, 0x100
	s_addc_u32 s7, s7, 0
	s_cmp_ge_i32 s8, s80
	s_mov_b32 s4, s8
	s_cbranch_scc0 .LBB0_431
